# attention loop software-pipelined across KV tiles (QK of tile j+1 with softmax of tile j in the MFMA gaps, then PV j) + GEMM DMA early issue
# speedup vs baseline: 1.0177x; 1.0079x over previous
; template <bool FIXED>
; DEVI void attn_task(const bf16_t* __restrict__ Qb, const bf16_t* __restrict__ Kh, const bf16_t* __restrict__ Vh, bf16_t* __restrict__ Ob, char* lds, float shiftC) {
;   const int tid = tid_(), wid = tid >> 6, lane = tid & 63, r32 = lane & 31, hi = lane >> 5;
;   const int wu = __builtin_amdgcn_readfirstlane(wid);
;   char* K_lds = lds; char* V_lds = lds + 24576;
;   float* wsf = (float*)(lds + 24576 + 16384) + wid * 64; float* li_l = wsf; float* al_l = wsf + 32;
;   float m_reg = -1e30f, l_reg = 0.f;
;   f32x16 o[4] = {};
;   bf16x8 qr[12];
;   {
;     const char* Qc = (const char*)Qb;
;     const unsigned qoff = (unsigned)((wid * 32 + r32) * 192 + hi * 8) * 2u;
; #pragma unroll
;     for (int d0 = 0; d0 < 12; ++d0) qr[d0] = *(const bf16x8*)(Qc + (qoff + d0 * 32));
;   }
;   const char* Kc = (const char*)Kh; const char* Vc = (const char*)Vh;
;   unsigned ksrc[6], vsrc[4];
; #pragma unroll
;   for (int e = 0; e < 6; ++e) {
;     const unsigned byte = (unsigned)((wu * 6 + e) * 1024 + lane * 16);
;     const unsigned r = byte / 384u, cpos = (byte - r * 384u) >> 4;
;     ksrc[e] = r * 384u + (((cpos & ~7u) | ((cpos & 7u) ^ ((r >> 1) & 7u))) << 4);
;   }
; #pragma unroll
;   for (int e = 0; e < 4; ++e) {
;     const int st = 2 * (wu * 4 + e) + (lane >> 5);
;     const int kk = (st >> 2) * 8 + ((lane & 31) >> 2), c = (st & 3) * 32 + (lane & 3) * 8;
;     const int k = (kk & ~0xC) | ((kk & 4) << 1) | ((kk & 8) >> 1);
;     vsrc[e] = (unsigned)(k * 256 + c * 2);
;   }
;     ...
;   const int vb0 = (int)(uintptr_t)V_lds + v_rd_base(lane);
;   const int swz = (r32 >> 1) & 7;
;   int kx[4];
; #pragma unroll
;   for (int i = 0; i < 4; ++i) kx[i] = ((2 * i + hi) ^ swz) << 4;
;   const char* Kr0 = K_lds + r32 * 384;
;   KISSUE(0); VISSUE(0); ABAR();
; template <int PH>
; DEVI void run_phase(const Params& p, char* lds) {
;     ...
;       const int bh = (v >> 9) * 8 + (v & 7), qb = (v & 511) >> 3;
;       const int b = bh >> 3, h = bh & 7;
;       const bf16_t* Qp = (const bf16_t*)(ws + OFF_X) + ((size_t)bh * SEQL + qb * 128) * 192;
;       const bf16_t* Kp = (const bf16_t*)(ws + OFF_K) + (size_t)bh * KVL * 192;
;       const bf16_t* Vp = (const bf16_t*)(ws + OFF_ACTA) + (size_t)bh * KVL * 128;
;       bf16_t* Op = (bf16_t*)(ws + OFF_ACTB) + ((size_t)(b * SEQL + qb * 128)) * LDP + h * 128;
.LBB0_1044:
	s_ashr_i32 s0, s88, 6
	s_and_b32 s2, s0, -8
	s_and_b32 s33, s88, 7
	s_or_b32 s0, s2, s33
	s_ashr_i32 s1, s0, 31
	s_lshl_b32 s26, s88, 4
	s_lshl_b64 s[6:7], s[0:1], 13
	s_and_b32 s1, s26, 0x1f80
	s_or_b32 s1, s6, s1
	s_mul_i32 s6, s7, 0x180
	s_mul_hi_u32 s7, s1, 0x180
	s_add_i32 s7, s7, s6
	s_mulk_i32 s1, 0x180
	s_add_u32 s8, s12, s1
	s_addc_u32 s9, s13, s7
	s_mul_i32 s6, s0, 0x318000
	s_mul_hi_i32 s1, s0, 0x318000
	s_add_u32 s6, s16, s6
	s_addc_u32 s7, s17, s1
	s_mul_hi_i32 s1, s0, 0x210000
	s_mul_i32 s0, s0, 0x210000
	s_add_u32 s0, s20, s0
	s_addc_u32 s1, s21, s1
	s_and_b32 s26, s26, 0xffffff80
	s_mul_hi_i32 s27, s26, 0x880
	s_mulk_i32 s26, 0x880
	s_add_u32 s26, s28, s26
	s_addc_u32 s27, s29, s27
	s_lshl_b32 s42, s33, 8
	s_add_u32 s42, s26, s42
	s_addc_u32 s43, s27, 0
	s_andn2_b64 vcc, exec, s[4:5]
	s_mov_b64 s[26:27], -1
	s_cbranch_vccnz .LBB0_1050
	v_mov_b32_e32 v177, v164
	v_mov_b32_e32 v34, 0
	v_ashrrev_i32_e32 v0, 6, v177
	v_and_b32_e32 v172, 31, v177
	v_lshlrev_b32_e32 v174, 5, v0
	v_or_b32_e32 v2, v174, v172
	v_bfe_u32 v173, v177, 5, 1
	v_mul_lo_u32 v2, v2, s3
	v_lshl_or_b32 v2, v173, 4, v2
	v_add_u32_e32 v3, 0x80, v2
	global_load_dwordx4 v[142:145], v2, s[8:9]
	global_load_dwordx4 v[138:141], v2, s[8:9] offset:32
	global_load_dwordx4 v[134:137], v2, s[8:9] offset:64
	global_load_dwordx4 v[126:129], v2, s[8:9] offset:96
	v_add_u32_e32 v4, 0xa0, v2
	global_load_dwordx4 v[130:133], v3, s[8:9]
	global_load_dwordx4 v[118:121], v4, s[8:9]
	v_add_u32_e32 v3, 0xc0, v2
	v_add_u32_e32 v4, 0xe0, v2
	global_load_dwordx4 v[122:125], v3, s[8:9]
	global_load_dwordx4 v[110:113], v4, s[8:9]
	v_add_u32_e32 v3, 0x100, v2
	v_and_b32_e32 v175, 63, v177
	v_add_u32_e32 v4, 0x120, v2
	global_load_dwordx4 v[114:117], v3, s[8:9]
	global_load_dwordx4 v[106:109], v4, s[8:9]
	v_add_u32_e32 v3, 0x140, v2
	v_readfirstlane_b32 s26, v0
	v_add_u32_e32 v2, 0x160, v2
	global_load_dwordx4 v[102:105], v3, s[8:9]
	global_load_dwordx4 v[98:101], v2, s[8:9]
	v_lshlrev_b32_e32 v3, 4, v175
	s_mul_i32 s27, s26, 0x1800
	v_or_b32_e32 v0, s27, v3
	v_mul_hi_u32 v2, v0, s45
	v_lshrrev_b32_e32 v8, 8, v2
	v_mul_u32_u24_e32 v4, 0x180, v8
	v_sub_u32_e32 v9, v0, v4
	v_lshrrev_b32_e32 v5, 4, v9
	v_lshrrev_b32_e32 v2, 9, v2
	v_bitop3_b32 v10, v5, 7, v2 bitop3:0x48
	v_and_or_b32 v2, v5, s46, v10
	v_or_b32_e32 v0, 0x400, v0
	v_lshl_add_u32 v4, v2, 4, v4
	v_mul_hi_u32 v2, v0, s45
	v_lshrrev_b32_e32 v11, 8, v2
	v_mul_u32_u24_e32 v5, 0x180, v11
	v_sub_u32_e32 v12, v0, v5
	v_lshrrev_b32_e32 v0, 4, v12
	v_lshrrev_b32_e32 v2, 9, v2
	v_bitop3_b32 v13, v0, 7, v2 bitop3:0x48
	v_and_or_b32 v0, v0, s46, v13
	s_add_i32 s54, s27, 0x800
	v_lshl_add_u32 v5, v0, 4, v5
	v_or_b32_e32 v0, s54, v3
	v_mul_hi_u32 v2, v0, s45
	v_lshrrev_b32_e32 v14, 8, v2
	v_mul_u32_u24_e32 v6, 0x180, v14
	v_sub_u32_e32 v15, v0, v6
	v_lshrrev_b32_e32 v0, 4, v15
	v_lshrrev_b32_e32 v2, 9, v2
	v_bitop3_b32 v16, v0, 7, v2 bitop3:0x48
	v_and_or_b32 v0, v0, s46, v16
	s_add_i32 s54, s27, 0xc00
	v_lshl_add_u32 v6, v0, 4, v6
	v_or_b32_e32 v0, s54, v3
	v_mul_hi_u32 v2, v0, s45
	v_lshrrev_b32_e32 v17, 8, v2
	v_mul_u32_u24_e32 v7, 0x180, v17
	v_sub_u32_e32 v18, v0, v7
	v_lshrrev_b32_e32 v0, 4, v18
	v_lshrrev_b32_e32 v2, 9, v2
	v_bitop3_b32 v19, v0, 7, v2 bitop3:0x48
	v_and_or_b32 v0, v0, s46, v19
	s_add_i32 s54, s27, 0x1000
	v_lshl_add_u32 v7, v0, 4, v7
	v_or_b32_e32 v0, s54, v3
	v_mul_hi_u32 v2, v0, s45
	v_lshrrev_b32_e32 v20, 8, v2
	v_mul_u32_u24_e32 v21, 0x180, v20
	v_sub_u32_e32 v22, v0, v21
	v_lshrrev_b32_e32 v0, 4, v22
	v_lshrrev_b32_e32 v2, 9, v2
	v_bitop3_b32 v23, v0, 7, v2 bitop3:0x48
	v_and_or_b32 v0, v0, s46, v23
	s_add_i32 s54, s27, 0x1400
	v_lshl_add_u32 v21, v0, 4, v21
	v_or_b32_e32 v0, s54, v3
	v_mul_hi_u32 v2, v0, s45
	v_lshrrev_b32_e32 v24, 8, v2
	v_mul_u32_u24_e32 v25, 0x180, v24
	v_sub_u32_e32 v26, v0, v25
	v_lshrrev_b32_e32 v0, 4, v26
	v_lshrrev_b32_e32 v2, 9, v2
	v_bitop3_b32 v27, v0, 7, v2 bitop3:0x48
	v_and_or_b32 v0, v0, s46, v27
	v_lshl_add_u32 v25, v0, 4, v25
	v_lshlrev_b32_e32 v0, 4, v177
	v_bfe_u32 v28, v177, 2, 2
	v_lshrrev_b32_e32 v29, 1, v177
	s_lshl_b32 s64, s26, 12
	s_add_i32 s26, s27, 0
	v_and_b32_e32 v2, 48, v0
	v_and_or_b32 v0, v29, 8, v28
	v_or_b32_e32 v32, 2, v173
	s_mov_b32 m0, s26
	s_add_i32 s27, s26, 0x400
	v_lshl_or_b32 v30, v173, 6, v2
	v_lshl_or_b32 v31, v0, 8, s64
	v_lshlrev_b32_e32 v32, 6, v32
	global_load_lds_dwordx4 v4, s[6:7]
	s_mov_b32 m0, s27
	s_add_i32 s54, s26, 0x800
	v_or_b32_e32 v0, v31, v30
	v_or3_b32 v2, v32, v2, v31
	v_lshlrev_b32_e32 v31, 3, v175
	v_and_b32_e32 v3, 0xc0, v3
	v_lshlrev_b32_e32 v32, 1, v177
	global_load_lds_dwordx4 v5, s[6:7]
	s_mov_b32 m0, s54
	s_add_i32 s55, s26, 0xc00
	s_add_i32 s56, s26, 0x1000
	s_add_i32 s57, s26, 0x1400
	v_and_or_b32 v3, v31, 24, v3
	v_and_b32_e32 v32, 32, v32
	v_and_b32_e32 v31, 0x100, v31
	global_load_lds_dwordx4 v6, s[6:7]
	s_mov_b32 m0, s55
	s_cmp_lg_u32 s53, -1
	v_or3_b32 v3, v3, v32, v31
	global_load_lds_dwordx4 v7, s[6:7]
	s_mov_b32 m0, s56
	s_cselect_b32 s58, s53, 0
	s_add_i32 s61, s64, 0
	global_load_lds_dwordx4 v21, s[6:7]
	s_mov_b32 m0, s57
	v_add_u32_e32 v176, s58, v3
	s_add_i32 s58, s61, 0x6000
	global_load_lds_dwordx4 v25, s[6:7]
	s_mov_b32 m0, s58
	s_add_i32 s59, s61, 0x6400
	v_lshl_add_u64 v[4:5], s[0:1], 0, v[0:1]
	global_load_lds_dwordx4 v0, s[0:1]
	v_mov_b32_e32 v3, v1
	s_mov_b32 m0, s59
	s_add_i32 s60, s61, 0x6800
	v_lshl_add_u64 v[6:7], s[0:1], 0, v[2:3]
	global_load_lds_dwordx4 v2, s[0:1]
	v_lshl_add_u64 v[2:3], v[4:5], 0, s[30:31]
	s_mov_b32 m0, s60
	s_addk_i32 s61, 0x6c00
	global_load_lds_dwordx4 v[2:3], off
	v_lshl_add_u64 v[2:3], v[6:7], 0, s[30:31]
	s_mov_b32 m0, s61
	s_add_i32 s65, s2, s33
; DEVI int v_rd_base(int lane) { return ((lane & 3) << 3) | (((lane >> 2) & 3) << 6) | (((lane >> 4) & 1) << 5) | (((lane >> 5) & 1) << 8); }
; #define KISSUE(k0) do { const char* kp_ = Kc + (size_t)(k0) * 384; _Pragma("unroll") for (int e = 0; e < 6; ++e) \
;       __builtin_amdgcn_global_load_lds((const unsigned*)(kp_ + ksrc[e]), (unsigned*)(K_lds + (wu * 6 + e) * 1024), 16, 0, 0); } while (0)
; template <bool FIXED>
; DEVI void attn_task(const bf16_t* __restrict__ Qb, const bf16_t* __restrict__ Kh, const bf16_t* __restrict__ Vh, bf16_t* __restrict__ Ob, char* lds, float shiftC) {
;     ...
;   float m_reg = -1e30f, l_reg = 0.f;
;   f32x16 o[4] = {};
;   bf16x8 qr[12];
;   {
;     const char* Qc = (const char*)Qb;
;     const unsigned qoff = (unsigned)((wid * 32 + r32) * 192 + hi * 8) * 2u;
; #pragma unroll
;     for (int d0 = 0; d0 < 12; ++d0) qr[d0] = *(const bf16x8*)(Qc + (qoff + d0 * 32));
;   }
;   const char* Kc = (const char*)Kh; const char* Vc = (const char*)Vh;
;   unsigned ksrc[6], vsrc[4];
; #pragma unroll
;   for (int e = 0; e < 6; ++e) {
;     const unsigned byte = (unsigned)((wu * 6 + e) * 1024 + lane * 16);
;     const unsigned r = byte / 384u, cpos = (byte - r * 384u) >> 4;
;     ksrc[e] = r * 384u + (((cpos & ~7u) | ((cpos & 7u) ^ ((r >> 1) & 7u))) << 4);
;   }
; #pragma unroll
;   for (int e = 0; e < 4; ++e) {
;     const int st = 2 * (wu * 4 + e) + (lane >> 5);
;     const int kk = (st >> 2) * 8 + ((lane & 31) >> 2), c = (st & 3) * 32 + (lane & 3) * 8;
;     const int k = (kk & ~0xC) | ((kk & 4) << 1) | ((kk & 8) >> 1);
;     vsrc[e] = (unsigned)(k * 256 + c * 2);
;   }
;     ...
;   const int vb0 = (int)(uintptr_t)V_lds + v_rd_base(lane);
;   const int swz = (r32 >> 1) & 7;
;   int kx[4];
; #pragma unroll
;   for (int i = 0; i < 4; ++i) kx[i] = ((2 * i + hi) ^ swz) << 4;
;   const char* Kr0 = K_lds + r32 * 384;
;   KISSUE(0); VISSUE(0); ABAR();
;   constexpr int NT = KVL / 64;
;   for (int j = 0; j < NT; ++j) {
;     f32x16 p0 = {}, p1 = {};
; #pragma unroll
;     for (int d0 = 0; d0 < 12; ++d0) {
;       const bf16x8 b0 = *(const bf16x8*)(Kr0 + (d0 >> 2) * 128 + kx[d0 & 3]);
;       const bf16x8 b1 = *(const bf16x8*)(Kr0 + 32 * 384 + (d0 >> 2) * 128 + kx[d0 & 3]);
;       p0 = __builtin_amdgcn_mfma_f32_32x32x16_bf16(b0, qr[d0], p0, 0, 0, 0);
;       p1 = __builtin_amdgcn_mfma_f32_32x32x16_bf16(b1, qr[d0], p1, 0, 0, 0);
;     }
	global_load_lds_dwordx4 v[2:3], off
	s_mul_i32 s69, s65, 0x210000
	v_lshlrev_b32_e32 v0, 7, v177
	s_mul_hi_i32 s68, s65, 0x210000
	s_add_u32 s62, s69, 0x34d0400
	v_and_b32_e32 v0, 0x800, v0
	v_lshlrev_b32_e32 v3, 8, v28
	s_addc_u32 s63, s68, 0
	v_or3_b32 v0, v0, s64, v3
	v_lshl_add_u64 v[146:147], s[62:63], 0, v[0:1]
	v_or_b32_e32 v0, v30, v0
	v_mad_i64_i32 v[148:149], s[62:63], s65, v171, v[0:1]
	s_add_u32 s62, s69, 0x34d0000
	s_addc_u32 s63, s68, 0
	v_or_b32_e32 v0, 0x80, v0
	v_lshl_add_u64 v[150:151], s[62:63], 0, v[0:1]
	s_mul_hi_i32 s63, s65, 0x318000
	s_mul_i32 s65, s65, 0x318000
	v_and_b32_e32 v0, 0xffffff80, v9
	s_add_u32 s62, s65, 0x16b52000
	v_mad_u32_u24 v0, v8, s3, v0
	s_addc_u32 s63, s63, 0
	v_lshl_or_b32 v0, v10, 4, v0
	v_lshl_add_u64 v[152:153], s[62:63], 0, v[0:1]
	v_and_b32_e32 v0, 0xffffff80, v12
	v_mad_u32_u24 v0, v11, s3, v0
	v_lshl_or_b32 v0, v13, 4, v0
	v_lshl_add_u64 v[154:155], s[62:63], 0, v[0:1]
	v_and_b32_e32 v0, 0xffffff80, v15
	v_mad_u32_u24 v0, v14, s3, v0
	v_lshl_or_b32 v0, v16, 4, v0
	v_lshl_add_u64 v[156:157], s[62:63], 0, v[0:1]
	v_and_b32_e32 v0, 0xffffff80, v18
	v_mad_u32_u24 v0, v17, s3, v0
	v_lshl_or_b32 v0, v19, 4, v0
	v_lshl_add_u64 v[158:159], s[62:63], 0, v[0:1]
	v_and_b32_e32 v0, 0xffffff80, v22
	v_mad_u32_u24 v0, v20, s3, v0
	v_lshl_or_b32 v0, v23, 4, v0
	v_lshl_add_u64 v[160:161], s[62:63], 0, v[0:1]
	v_and_b32_e32 v0, 0xffffff80, v26
	v_bfe_u32 v31, v177, 1, 3
	v_mad_u32_u24 v0, v24, s3, v0
	v_bitop3_b32 v29, v173, v29, 7 bitop3:0x78
	v_bitop3_b32 v32, v173, v31, 2 bitop3:0x36
	v_bitop3_b32 v33, v173, v31, 4 bitop3:0x36
	v_bitop3_b32 v31, v173, v31, 6 bitop3:0x36
	s_waitcnt vmcnt(0) lgkmcnt(0)
	v_lshl_or_b32 v0, v27, 4, v0
	v_lshlrev_b32_e32 v29, 4, v29
	v_lshlrev_b32_e32 v32, 4, v32
	v_lshlrev_b32_e32 v33, 4, v33
	v_lshlrev_b32_e32 v31, 4, v31
	v_mad_u32_u24 v2, v172, s3, 0
	v_lshl_add_u64 v[162:163], s[62:63], 0, v[0:1]
	v_mov_b32_e32 v0, 0
	v_or3_b32 v146, v30, v146, s44
	s_movk_i32 s62, 0x83
	v_add_u32_e32 v181, v2, v29
	v_add_u32_e32 v180, v2, v32
	v_add_u32_e32 v179, v2, v33
	v_add_u32_e32 v178, v2, v31
	v_mov_b32_e32 v2, 0
	v_mov_b32_e32 v3, v0
	v_mov_b32_e32 v4, v0
	v_mov_b32_e32 v5, v0
	v_mov_b32_e32 v6, v0
	v_mov_b32_e32 v7, v0
	v_mov_b32_e32 v8, v0
	v_mov_b32_e32 v9, v0
	v_mov_b32_e32 v10, v0
	v_mov_b32_e32 v11, v0
	v_mov_b32_e32 v12, v0
	v_mov_b32_e32 v13, v0
	v_mov_b32_e32 v14, v0
	v_mov_b32_e32 v15, v0
	v_mov_b32_e32 v16, v0
	v_mov_b32_e32 v17, v0
	v_mov_b32_e32 v18, 0
	v_mov_b32_e32 v19, v0
	v_mov_b32_e32 v20, v0
	v_mov_b32_e32 v21, v0
	v_mov_b32_e32 v22, v0
	v_mov_b32_e32 v23, v0
	v_mov_b32_e32 v24, v0
	v_mov_b32_e32 v25, v0
	v_mov_b32_e32 v26, v0
	v_mov_b32_e32 v27, v0
	v_mov_b32_e32 v28, v0
	v_mov_b32_e32 v29, v0
	v_mov_b32_e32 v30, v0
	v_mov_b32_e32 v31, v0
	v_mov_b32_e32 v32, v0
	v_mov_b32_e32 v33, v0
	v_mov_b32_e32 v35, v0
	v_mov_b32_e32 v36, v0
	v_mov_b32_e32 v37, v0
	v_mov_b32_e32 v38, v0
	v_mov_b32_e32 v39, v0
	v_mov_b32_e32 v40, v0
	v_mov_b32_e32 v41, v0
	v_mov_b32_e32 v42, v0
	v_mov_b32_e32 v43, v0
	v_mov_b32_e32 v44, v0
	v_mov_b32_e32 v45, v0
	v_mov_b32_e32 v46, v0
	v_mov_b32_e32 v47, v0
	v_mov_b32_e32 v48, v0
	v_mov_b32_e32 v49, v0
	v_mov_b32_e32 v50, 0
	v_mov_b32_e32 v51, v0
	v_mov_b32_e32 v52, v0
	v_mov_b32_e32 v53, v0
	v_mov_b32_e32 v54, v0
	v_mov_b32_e32 v55, v0
	v_mov_b32_e32 v56, v0
	v_mov_b32_e32 v57, v0
	v_mov_b32_e32 v58, v0
	v_mov_b32_e32 v59, v0
	v_mov_b32_e32 v60, v0
	v_mov_b32_e32 v61, v0
	v_mov_b32_e32 v62, v0
	v_mov_b32_e32 v63, v0
	v_mov_b32_e32 v64, v0
	v_mov_b32_e32 v65, v0
	s_barrier
	s_waitcnt vmcnt(0)
	ds_read_b128 v[186:189], v181
	ds_read_b128 v[190:193], v180
	ds_read_b128 v[194:197], v179
	ds_read_b128 v[198:201], v178
	ds_read_b128 v[202:205], v181 offset:128
	ds_read_b128 v[206:209], v180 offset:128
	s_waitcnt lgkmcnt(5)
	v_mfma_f32_32x32x16_bf16 v[66:81], v[186:189], v[142:145], 0
	ds_read_b128 v[186:189], v179 offset:128
	s_waitcnt lgkmcnt(5)
	v_mfma_f32_32x32x16_bf16 v[66:81], v[190:193], v[138:141], v[66:81]
	ds_read_b128 v[190:193], v178 offset:128
	s_waitcnt lgkmcnt(5)
	v_mfma_f32_32x32x16_bf16 v[66:81], v[194:197], v[134:137], v[66:81]
	ds_read_b128 v[194:197], v181 offset:256
	s_waitcnt lgkmcnt(5)
	v_mfma_f32_32x32x16_bf16 v[66:81], v[198:201], v[126:129], v[66:81]
	ds_read_b128 v[198:201], v180 offset:256
	s_waitcnt lgkmcnt(5)
	v_mfma_f32_32x32x16_bf16 v[66:81], v[202:205], v[130:133], v[66:81]
	ds_read_b128 v[202:205], v179 offset:256
	s_waitcnt lgkmcnt(5)
	v_mfma_f32_32x32x16_bf16 v[66:81], v[206:209], v[118:121], v[66:81]
	ds_read_b128 v[206:209], v178 offset:256
	s_waitcnt lgkmcnt(5)
	v_mfma_f32_32x32x16_bf16 v[66:81], v[186:189], v[122:125], v[66:81]
	ds_read_b128 v[186:189], v181 offset:12288
	s_waitcnt lgkmcnt(5)
	v_mfma_f32_32x32x16_bf16 v[66:81], v[190:193], v[110:113], v[66:81]
	ds_read_b128 v[190:193], v180 offset:12288
	s_waitcnt lgkmcnt(5)
	v_mfma_f32_32x32x16_bf16 v[66:81], v[194:197], v[114:117], v[66:81]
	ds_read_b128 v[194:197], v179 offset:12288
	s_waitcnt lgkmcnt(5)
	v_mfma_f32_32x32x16_bf16 v[66:81], v[198:201], v[106:109], v[66:81]
	ds_read_b128 v[198:201], v178 offset:12288
	s_waitcnt lgkmcnt(5)
	v_mfma_f32_32x32x16_bf16 v[66:81], v[202:205], v[102:105], v[66:81]
	ds_read_b128 v[202:205], v181 offset:12416
	s_waitcnt lgkmcnt(5)
	v_mfma_f32_32x32x16_bf16 v[66:81], v[206:209], v[98:101], v[66:81]
	ds_read_b128 v[206:209], v180 offset:12416
	s_waitcnt lgkmcnt(5)
	v_mfma_f32_32x32x16_bf16 v[82:97], v[186:189], v[142:145], 0
	ds_read_b128 v[186:189], v179 offset:12416
	s_waitcnt lgkmcnt(5)
	v_mfma_f32_32x32x16_bf16 v[82:97], v[190:193], v[138:141], v[82:97]
	ds_read_b128 v[190:193], v178 offset:12416
	s_waitcnt lgkmcnt(5)
	v_mfma_f32_32x32x16_bf16 v[82:97], v[194:197], v[134:137], v[82:97]
	ds_read_b128 v[194:197], v181 offset:12544
	s_waitcnt lgkmcnt(5)
	v_mfma_f32_32x32x16_bf16 v[82:97], v[198:201], v[126:129], v[82:97]
	ds_read_b128 v[198:201], v180 offset:12544
	s_waitcnt lgkmcnt(5)
	v_mfma_f32_32x32x16_bf16 v[82:97], v[202:205], v[130:133], v[82:97]
	ds_read_b128 v[202:205], v179 offset:12544
	s_waitcnt lgkmcnt(5)
	v_mfma_f32_32x32x16_bf16 v[82:97], v[206:209], v[118:121], v[82:97]
	ds_read_b128 v[206:209], v178 offset:12544
	s_waitcnt lgkmcnt(5)
	v_mfma_f32_32x32x16_bf16 v[82:97], v[186:189], v[122:125], v[82:97]
	s_waitcnt lgkmcnt(4)
	v_mfma_f32_32x32x16_bf16 v[82:97], v[190:193], v[110:113], v[82:97]
	s_waitcnt lgkmcnt(3)
	v_mfma_f32_32x32x16_bf16 v[82:97], v[194:197], v[114:117], v[82:97]
	s_waitcnt lgkmcnt(2)
	v_mfma_f32_32x32x16_bf16 v[82:97], v[198:201], v[106:109], v[82:97]
	s_waitcnt lgkmcnt(1)
	v_mfma_f32_32x32x16_bf16 v[82:97], v[202:205], v[102:105], v[82:97]
	s_waitcnt lgkmcnt(0)
	v_mfma_f32_32x32x16_bf16 v[82:97], v[206:209], v[98:101], v[82:97]
	s_waitcnt lgkmcnt(0)
	s_barrier
; DEVI int crow(int r, int hi) { return (r & 3) + 8 * (r >> 2) + 4 * hi; }
; DEVI int v_rd_base(int lane) { return ((lane & 3) << 3) | (((lane >> 2) & 3) << 6) | (((lane >> 4) & 1) << 5) | (((lane >> 5) & 1) << 8); }
; #define ABAR() do { asm volatile("s_waitcnt vmcnt(0) lgkmcnt(0)" ::: "memory"); __builtin_amdgcn_s_barrier(); } while (0)
; template <bool FIXED>
; DEVI void attn_task(const bf16_t* __restrict__ Qb, const bf16_t* __restrict__ Kh, const bf16_t* __restrict__ Vh, bf16_t* __restrict__ Ob, char* lds, float shiftC) {
;     ...
;   const int vb0 = (int)(uintptr_t)V_lds + v_rd_base(lane);
;   const int swz = (r32 >> 1) & 7;
;   int kx[4];
; #pragma unroll
;   for (int i = 0; i < 4; ++i) kx[i] = ((2 * i + hi) ^ swz) << 4;
;   const char* Kr0 = K_lds + r32 * 384;
;   KISSUE(0); VISSUE(0); ABAR();
;   constexpr int NT = KVL / 64;
;   for (int j = 0; j < NT; ++j) {
;     f32x16 p0 = {}, p1 = {};
; #pragma unroll
;     for (int d0 = 0; d0 < 12; ++d0) {
;       const bf16x8 b0 = *(const bf16x8*)(Kr0 + (d0 >> 2) * 128 + kx[d0 & 3]);
;       const bf16x8 b1 = *(const bf16x8*)(Kr0 + 32 * 384 + (d0 >> 2) * 128 + kx[d0 & 3]);
;       p0 = __builtin_amdgcn_mfma_f32_32x32x16_bf16(b0, qr[d0], p0, 0, 0, 0);
;       p1 = __builtin_amdgcn_mfma_f32_32x32x16_bf16(b1, qr[d0], p1, 0, 0, 0);
;     }
;     ABAR();
;     if (j + 1 < NT) KISSUE((j + 1) * 64);
;     float mn, alpha = 1.f;
;     if constexpr (FIXED) {
; #pragma unroll
;       for (int r = 0; r < 16; ++r) p0[r] = __builtin_amdgcn_exp2f(p0[r]);
; #pragma unroll
;       for (int r = 0; r < 16; ++r) p1[r] = __builtin_amdgcn_exp2f(p1[r]);
;     } else partialSM(p0, p1, m_reg, mn, alpha);
;     if (!FIXED && __any(alpha < 1.f)) {
;       if (hi == 0) al_l[r32] = alpha;
;       asm volatile("s_waitcnt lgkmcnt(0)" ::: "memory");
; #pragma unroll
;       for (int r = 0; r < 16; ++r) { const float a = al_l[crow(r, hi)];
; #pragma unroll
;         for (int d = 0; d < 4; ++d) o[d][r] *= a; }
;     }
;     bf16x8 pa0, pa1, pa2, pa3;
;     finishSM(p0, p1, alpha, l_reg, pa0, pa1, pa2, pa3);
;     pv_one<0>(o[0], vb0, pa0, pa1, pa2, pa3); pv_one<1>(o[1], vb0, pa0, pa1, pa2, pa3);
;     pv_one<2>(o[2], vb0, pa0, pa1, pa2, pa3); pv_one<3>(o[3], vb0, pa0, pa1, pa2, pa3);
;     ABAR();
;     if (j + 1 < NT) VISSUE((j + 1) * 64);
;   }
	v_add_u32_e32 v242, 0x34d0000, v148
	v_add_u32_e32 v243, 0x34cfc00, v148
	v_add_u32_e32 v150, 0xfffffc00, v150
	v_add_u32_e32 v146, 0xfffff400, v146
	v_add_u32_e32 v154, 0xfffffc00, v154
	v_add_u32_e32 v156, 0xfffff800, v156
	v_add_u32_e32 v158, 0xfffff400, v158
	v_add_u32_e32 v162, 0xfffffc00, v162
	s_mov_b32 m0, s26
	s_nop 0
	global_load_lds_dwordx4 v152, s[24:25]
	global_load_lds_dwordx4 v154, s[24:25] offset:1024
	global_load_lds_dwordx4 v156, s[24:25] offset:2048
	global_load_lds_dwordx4 v158, s[24:25] offset:3072
	s_mov_b32 m0, s56
	s_nop 0
	global_load_lds_dwordx4 v160, s[24:25]
	global_load_lds_dwordx4 v162, s[24:25] offset:1024
	s_add_u32 s98, s24, 0x6000
	s_addc_u32 s99, s25, 0
	s_mov_b32 s100, s24
	s_mov_b32 s101, s25
	s_waitcnt vmcnt(0)
	s_barrier
	ds_read_b128 v[186:189], v181
	ds_read_b128 v[190:193], v180
	ds_read_b128 v[194:197], v179
	ds_read_b128 v[198:201], v178
	ds_read_b128 v[202:205], v181 offset:128
	ds_read_b128 v[206:209], v180 offset:128
.Lat7_top:
	s_waitcnt lgkmcnt(5)
	v_mfma_f32_32x32x16_bf16 v[210:225], v[186:189], v[142:145], 0
	ds_read_b128 v[186:189], v179 offset:128
	v_exp_f32_e32 v66, v66
	v_exp_f32_e32 v67, v67
	v_exp_f32_e32 v68, v68
	v_exp_f32_e32 v69, v69
	s_waitcnt lgkmcnt(5)
	v_mfma_f32_32x32x16_bf16 v[210:225], v[190:193], v[138:141], v[210:225]
	ds_read_b128 v[190:193], v178 offset:128
	v_exp_f32_e32 v70, v70
	v_add_f32_e32 v182, 0, v66
	v_exp_f32_e32 v71, v71
	v_add_f32_e32 v182, v67, v182
	s_waitcnt lgkmcnt(5)
	v_mfma_f32_32x32x16_bf16 v[210:225], v[194:197], v[134:137], v[210:225]
	ds_read_b128 v[194:197], v181 offset:256
	v_exp_f32_e32 v72, v72
	v_add_f32_e32 v182, v68, v182
	v_exp_f32_e32 v73, v73
	v_add_f32_e32 v182, v69, v182
	s_waitcnt lgkmcnt(5)
	v_mfma_f32_32x32x16_bf16 v[210:225], v[198:201], v[126:129], v[210:225]
	ds_read_b128 v[198:201], v180 offset:256
	v_exp_f32_e32 v74, v74
	v_add_f32_e32 v182, v70, v182
	v_exp_f32_e32 v75, v75
	v_add_f32_e32 v182, v71, v182
	s_waitcnt lgkmcnt(5)
	v_mfma_f32_32x32x16_bf16 v[210:225], v[202:205], v[130:133], v[210:225]
	ds_read_b128 v[202:205], v179 offset:256
	v_exp_f32_e32 v76, v76
	v_add_f32_e32 v182, v72, v182
	v_exp_f32_e32 v77, v77
	v_add_f32_e32 v182, v73, v182
	s_waitcnt lgkmcnt(5)
	v_mfma_f32_32x32x16_bf16 v[210:225], v[206:209], v[118:121], v[210:225]
	ds_read_b128 v[206:209], v178 offset:256
	v_exp_f32_e32 v78, v78
	v_add_f32_e32 v182, v74, v182
	v_exp_f32_e32 v79, v79
	v_add_f32_e32 v182, v75, v182
	s_waitcnt lgkmcnt(5)
	v_mfma_f32_32x32x16_bf16 v[210:225], v[186:189], v[122:125], v[210:225]
	ds_read_b128 v[186:189], v181 offset:12288
	v_exp_f32_e32 v80, v80
	v_add_f32_e32 v182, v76, v182
	v_exp_f32_e32 v81, v81
	v_add_f32_e32 v182, v77, v182
	s_waitcnt lgkmcnt(5)
	v_mfma_f32_32x32x16_bf16 v[210:225], v[190:193], v[110:113], v[210:225]
	ds_read_b128 v[190:193], v180 offset:12288
	v_add_f32_e32 v182, v78, v182
	v_add_f32_e32 v182, v79, v182
	v_add_f32_e32 v182, v80, v182
	v_add_f32_e32 v182, v81, v182
	s_waitcnt lgkmcnt(5)
	v_mfma_f32_32x32x16_bf16 v[210:225], v[194:197], v[114:117], v[210:225]
	ds_read_b128 v[194:197], v179 offset:12288
	v_cvt_pk_bf16_f32 v66, v66, v67
	v_cvt_pk_bf16_f32 v67, v68, v69
	v_cvt_pk_bf16_f32 v68, v70, v71
	v_cvt_pk_bf16_f32 v69, v72, v73
	s_waitcnt lgkmcnt(5)
	v_mfma_f32_32x32x16_bf16 v[210:225], v[198:201], v[106:109], v[210:225]
	ds_read_b128 v[198:201], v178 offset:12288
	v_cvt_pk_bf16_f32 v70, v74, v75
	v_cvt_pk_bf16_f32 v71, v76, v77
	v_cvt_pk_bf16_f32 v72, v78, v79
	v_cvt_pk_bf16_f32 v73, v80, v81
	s_waitcnt lgkmcnt(5)
	v_mfma_f32_32x32x16_bf16 v[210:225], v[202:205], v[102:105], v[210:225]
	ds_read_b128 v[202:205], v181 offset:12416
	v_permlane32_swap_b32_e32 v66, v68
	v_permlane32_swap_b32_e32 v67, v69
	v_exp_f32_e32 v82, v82
	v_exp_f32_e32 v83, v83
	s_waitcnt lgkmcnt(5)
	v_mfma_f32_32x32x16_bf16 v[210:225], v[206:209], v[98:101], v[210:225]
	ds_read_b128 v[206:209], v180 offset:12416
	v_exp_f32_e32 v84, v84
	v_permlane32_swap_b32_e32 v70, v72
	v_permlane32_swap_b32_e32 v71, v73
	v_exp_f32_e32 v85, v85
	s_waitcnt lgkmcnt(5)
	v_mfma_f32_32x32x16_bf16 v[226:241], v[186:189], v[142:145], 0
	ds_read_b128 v[186:189], v179 offset:12416
	v_exp_f32_e32 v86, v86
	v_add_f32_e32 v182, v82, v182
	v_exp_f32_e32 v87, v87
	v_add_f32_e32 v182, v83, v182
	s_waitcnt lgkmcnt(5)
	v_mfma_f32_32x32x16_bf16 v[226:241], v[190:193], v[138:141], v[226:241]
	ds_read_b128 v[190:193], v178 offset:12416
	v_exp_f32_e32 v88, v88
	v_add_f32_e32 v182, v84, v182
	v_exp_f32_e32 v89, v89
	v_add_f32_e32 v182, v85, v182
	s_waitcnt lgkmcnt(5)
	v_mfma_f32_32x32x16_bf16 v[226:241], v[194:197], v[134:137], v[226:241]
	ds_read_b128 v[194:197], v181 offset:12544
	v_exp_f32_e32 v90, v90
	v_add_f32_e32 v182, v86, v182
	v_exp_f32_e32 v91, v91
	v_add_f32_e32 v182, v87, v182
	s_waitcnt lgkmcnt(5)
	v_mfma_f32_32x32x16_bf16 v[226:241], v[198:201], v[126:129], v[226:241]
	ds_read_b128 v[198:201], v180 offset:12544
	v_exp_f32_e32 v92, v92
	v_add_f32_e32 v182, v88, v182
	v_exp_f32_e32 v93, v93
	v_add_f32_e32 v182, v89, v182
	s_waitcnt lgkmcnt(5)
	v_mfma_f32_32x32x16_bf16 v[226:241], v[202:205], v[130:133], v[226:241]
	ds_read_b128 v[202:205], v179 offset:12544
	v_exp_f32_e32 v94, v94
	v_add_f32_e32 v182, v90, v182
	v_exp_f32_e32 v95, v95
	v_add_f32_e32 v182, v91, v182
	s_waitcnt lgkmcnt(5)
	v_mfma_f32_32x32x16_bf16 v[226:241], v[206:209], v[118:121], v[226:241]
	ds_read_b128 v[206:209], v178 offset:12544
	v_exp_f32_e32 v96, v96
	v_add_f32_e32 v182, v92, v182
	v_exp_f32_e32 v97, v97
	v_add_f32_e32 v182, v93, v182
	s_waitcnt lgkmcnt(5)
	v_mfma_f32_32x32x16_bf16 v[226:241], v[186:189], v[122:125], v[226:241]
	s_waitcnt vmcnt(0) lgkmcnt(0)
	s_barrier
	s_cmp_eq_u32 s62, 1
	s_cbranch_scc1 .Lat7_e_nok
	s_mov_b32 m0, s26
	s_nop 0
	global_load_lds_dwordx4 v152, s[98:99]
	global_load_lds_dwordx4 v154, s[98:99] offset:1024
	global_load_lds_dwordx4 v156, s[98:99] offset:2048
	global_load_lds_dwordx4 v158, s[98:99] offset:3072
	s_mov_b32 m0, s56
	s_nop 0
	global_load_lds_dwordx4 v160, s[98:99]
	global_load_lds_dwordx4 v162, s[98:99] offset:1024
	s_add_u32 s98, s98, 0x6000
	s_addc_u32 s99, s99, 0
; DEVI void finishSM(f32x16& p0, f32x16& p1, float alpha, float& l_reg, bf16x8& pa0, bf16x8& pa1, bf16x8& pa2, bf16x8& pa3) {
;   float ps = 0;
; #pragma unroll
;   for (int r = 0; r < 16; ++r) ps += p0[r];
; #pragma unroll
;   for (int r = 0; r < 16; ++r) ps += p1[r];
;   { auto rr = __builtin_amdgcn_permlane32_swap(__float_as_uint(ps), __float_as_uint(ps), false, false);
;     ps = __uint_as_float(rr[0]) + __uint_as_float(rr[1]); }
;   l_reg = l_reg * alpha + ps;
;     ...
;   PK4(p0, 0, pa0); PK4(p0, 8, pa1); PK4(p1, 0, pa2); PK4(p1, 8, pa3);
;     ...
; }
; DEVI int v_st(int k) { const int kk = (k & ~0xC) | ((k & 4) << 1) | ((k & 8) >> 1); return ((kk >> 3) * 4) * 512 + ((kk & 7) * 32) * 2; }
; DEVI int v_rd_base(int lane) { return ((lane & 3) << 3) | (((lane >> 2) & 3) << 6) | (((lane >> 4) & 1) << 5) | (((lane >> 5) & 1) << 8); }
; template <int OFF> DEVI s16x4 tr_read(int vb) {
;   s16x4 r; asm volatile("ds_read_b64_tr_b16 %0, %1 offset:%2" : "=&v"(r) : "v"(vb), "i"(OFF) : "memory"); return r;
; }
; template <int D0> DEVI void pv_one(f32x16& od, int vb, bf16x8 pa0, bf16x8 pa1, bf16x8 pa2, bf16x8 pa3) {
;   const s16x4 l0 = tr_read<v_rd_off(D0, 0, 0)>(vb), h0 = tr_read<v_rd_off(D0, 0, 1)>(vb), l1 = tr_read<v_rd_off(D0, 1, 0)>(vb), h1 = tr_read<v_rd_off(D0, 1, 1)>(vb);
;   const s16x4 l2 = tr_read<v_rd_off(D0, 2, 0)>(vb), h2 = tr_read<v_rd_off(D0, 2, 1)>(vb), l3 = tr_read<v_rd_off(D0, 3, 0)>(vb), h3 = tr_read<v_rd_off(D0, 3, 1)>(vb);
;   asm volatile("s_waitcnt lgkmcnt(0)" ::: "memory"); SBAR();
;     ...
;   od = __builtin_amdgcn_mfma_f32_32x32x16_bf16(pa0, PK(l0, h0), od, 0, 0, 0);
;   od = __builtin_amdgcn_mfma_f32_32x32x16_bf16(pa1, PK(l1, h1), od, 0, 0, 0);
;   od = __builtin_amdgcn_mfma_f32_32x32x16_bf16(pa2, PK(l2, h2), od, 0, 0, 0);
;   od = __builtin_amdgcn_mfma_f32_32x32x16_bf16(pa3, PK(l3, h3), od, 0, 0, 0);
;     ...
; }
; template <bool FIXED>
; DEVI void attn_task(const bf16_t* __restrict__ Qb, const bf16_t* __restrict__ Kh, const bf16_t* __restrict__ Vh, bf16_t* __restrict__ Ob, char* lds, float shiftC) {
;     ...
;   for (int j = 0; j < NT; ++j) {
;     f32x16 p0 = {}, p1 = {};
; #pragma unroll
;     for (int d0 = 0; d0 < 12; ++d0) {
;       const bf16x8 b0 = *(const bf16x8*)(Kr0 + (d0 >> 2) * 128 + kx[d0 & 3]);
;       const bf16x8 b1 = *(const bf16x8*)(Kr0 + 32 * 384 + (d0 >> 2) * 128 + kx[d0 & 3]);
;       p0 = __builtin_amdgcn_mfma_f32_32x32x16_bf16(b0, qr[d0], p0, 0, 0, 0);
.Lat7_e_nok:
	v_add_f32_e32 v182, v94, v182
	v_add_f32_e32 v182, v95, v182
	v_add_f32_e32 v182, v96, v182
	ds_read_b64_tr_b16 v[186:187], v176 offset:4096
	ds_read_b64_tr_b16 v[188:189], v176 offset:6144
	v_mfma_f32_32x32x16_bf16 v[226:241], v[190:193], v[110:113], v[226:241]
	v_add_f32_e32 v182, v97, v182
	v_cvt_pk_bf16_f32 v74, v82, v83
	v_cvt_pk_bf16_f32 v75, v84, v85
	ds_read_b64_tr_b16 v[190:191], v176 offset:4608
	ds_read_b64_tr_b16 v[192:193], v176 offset:6656
	v_mfma_f32_32x32x16_bf16 v[226:241], v[194:197], v[114:117], v[226:241]
	v_cvt_pk_bf16_f32 v76, v86, v87
	v_cvt_pk_bf16_f32 v77, v88, v89
	v_cvt_pk_bf16_f32 v78, v90, v91
	ds_read_b64_tr_b16 v[194:195], v176 offset:0
	ds_read_b64_tr_b16 v[196:197], v176 offset:2048
	v_mfma_f32_32x32x16_bf16 v[226:241], v[198:201], v[106:109], v[226:241]
	v_cvt_pk_bf16_f32 v79, v92, v93
	v_cvt_pk_bf16_f32 v80, v94, v95
	v_cvt_pk_bf16_f32 v81, v96, v97
	ds_read_b64_tr_b16 v[198:199], v176 offset:512
	ds_read_b64_tr_b16 v[200:201], v176 offset:2560
	v_mfma_f32_32x32x16_bf16 v[226:241], v[202:205], v[102:105], v[226:241]
	v_add_f32_e32 v0, v0, v182
	v_permlane32_swap_b32_e32 v74, v76
	v_permlane32_swap_b32_e32 v75, v77
	ds_read_b64_tr_b16 v[202:203], v176 offset:1024
	ds_read_b64_tr_b16 v[204:205], v176 offset:3072
	v_mfma_f32_32x32x16_bf16 v[226:241], v[206:209], v[98:101], v[226:241]
	v_permlane32_swap_b32_e32 v78, v80
	v_permlane32_swap_b32_e32 v79, v81
	ds_read_b64_tr_b16 v[206:207], v176 offset:1536
	ds_read_b64_tr_b16 v[208:209], v176 offset:3584
	s_waitcnt lgkmcnt(6)
	v_mfma_f32_32x32x16_bf16 v[50:65], v[66:69], v[194:197], v[50:65]
	ds_read_b64_tr_b16 v[194:195], v176 offset:5120
	ds_read_b64_tr_b16 v[196:197], v176 offset:7168
	s_waitcnt lgkmcnt(6)
	v_mfma_f32_32x32x16_bf16 v[34:49], v[66:69], v[198:201], v[34:49]
	ds_read_b64_tr_b16 v[198:199], v176 offset:5632
	ds_read_b64_tr_b16 v[200:201], v176 offset:7680
	s_waitcnt lgkmcnt(6)
	v_mfma_f32_32x32x16_bf16 v[18:33], v[66:69], v[202:205], v[18:33]
	ds_read_b64_tr_b16 v[202:203], v176 offset:8192
	ds_read_b64_tr_b16 v[204:205], v176 offset:10240
	s_waitcnt lgkmcnt(6)
	v_mfma_f32_32x32x16_bf16 v[2:17], v[66:69], v[206:209], v[2:17]
	ds_read_b64_tr_b16 v[206:207], v176 offset:8704
	ds_read_b64_tr_b16 v[208:209], v176 offset:10752
	v_mfma_f32_32x32x16_bf16 v[50:65], v[70:73], v[186:189], v[50:65]
	ds_read_b64_tr_b16 v[186:187], v176 offset:9216
	ds_read_b64_tr_b16 v[188:189], v176 offset:11264
	v_mfma_f32_32x32x16_bf16 v[34:49], v[70:73], v[190:193], v[34:49]
	ds_read_b64_tr_b16 v[190:191], v176 offset:9728
	ds_read_b64_tr_b16 v[192:193], v176 offset:11776
	s_waitcnt lgkmcnt(10)
	v_mfma_f32_32x32x16_bf16 v[18:33], v[70:73], v[194:197], v[18:33]
	ds_read_b64_tr_b16 v[194:195], v176 offset:12288
	ds_read_b64_tr_b16 v[196:197], v176 offset:14336
	s_waitcnt lgkmcnt(10)
	v_mfma_f32_32x32x16_bf16 v[2:17], v[70:73], v[198:201], v[2:17]
	ds_read_b64_tr_b16 v[198:199], v176 offset:12800
	ds_read_b64_tr_b16 v[200:201], v176 offset:14848
	s_waitcnt lgkmcnt(10)
	v_mfma_f32_32x32x16_bf16 v[50:65], v[74:77], v[202:205], v[50:65]
	ds_read_b64_tr_b16 v[202:203], v176 offset:13312
	ds_read_b64_tr_b16 v[204:205], v176 offset:15360
	s_waitcnt lgkmcnt(10)
	v_mfma_f32_32x32x16_bf16 v[34:49], v[74:77], v[206:209], v[34:49]
	ds_read_b64_tr_b16 v[206:207], v176 offset:13824
	ds_read_b64_tr_b16 v[208:209], v176 offset:15872
	s_waitcnt lgkmcnt(10)
	v_mfma_f32_32x32x16_bf16 v[18:33], v[74:77], v[186:189], v[18:33]
	s_waitcnt lgkmcnt(8)
	v_mfma_f32_32x32x16_bf16 v[2:17], v[74:77], v[190:193], v[2:17]
	s_waitcnt lgkmcnt(6)
	v_mfma_f32_32x32x16_bf16 v[50:65], v[78:81], v[194:197], v[50:65]
	s_waitcnt vmcnt(0) lgkmcnt(0)
	s_barrier
	s_mov_b32 m0, s58
	ds_read_b128 v[186:189], v181
	global_load_lds_dwordx4 v242, s[100:101]
	global_load_lds_dwordx4 v150, s[100:101] offset:1024
	global_load_lds_dwordx4 v243, s[100:101] offset:2048
	global_load_lds_dwordx4 v146, s[100:101] offset:3072
	s_add_u32 s100, s100, 0x4000
	s_addc_u32 s101, s101, 0
	ds_read_b128 v[190:193], v180
	ds_read_b128 v[194:197], v179
	v_mfma_f32_32x32x16_bf16 v[34:49], v[78:81], v[198:201], v[34:49]
	ds_read_b128 v[198:201], v178
	v_mfma_f32_32x32x16_bf16 v[18:33], v[78:81], v[202:205], v[18:33]
	ds_read_b128 v[202:205], v181 offset:128
	v_mfma_f32_32x32x16_bf16 v[2:17], v[78:81], v[206:209], v[2:17]
	ds_read_b128 v[206:209], v180 offset:128
	s_add_i32 s62, s62, -1
	s_cmp_eq_u32 s62, 0
	s_cbranch_scc1 .Lat7_done
; #define KISSUE(k0) do { const char* kp_ = Kc + (size_t)(k0) * 384; _Pragma("unroll") for (int e = 0; e < 6; ++e) \
;       __builtin_amdgcn_global_load_lds((const unsigned*)(kp_ + ksrc[e]), (unsigned*)(K_lds + (wu * 6 + e) * 1024), 16, 0, 0); } while (0)
; #define ABAR() do { asm volatile("s_waitcnt vmcnt(0) lgkmcnt(0)" ::: "memory"); __builtin_amdgcn_s_barrier(); } while (0)
; DEVI void finishSM(f32x16& p0, f32x16& p1, float alpha, float& l_reg, bf16x8& pa0, bf16x8& pa1, bf16x8& pa2, bf16x8& pa3) {
;   float ps = 0;
; #pragma unroll
;   for (int r = 0; r < 16; ++r) ps += p0[r];
; #pragma unroll
;   for (int r = 0; r < 16; ++r) ps += p1[r];
;   { auto rr = __builtin_amdgcn_permlane32_swap(__float_as_uint(ps), __float_as_uint(ps), false, false);
;     ps = __uint_as_float(rr[0]) + __uint_as_float(rr[1]); }
;   l_reg = l_reg * alpha + ps;
;     ...
;   PK4(p0, 0, pa0); PK4(p0, 8, pa1); PK4(p1, 0, pa2); PK4(p1, 8, pa3);
; template <bool FIXED>
; DEVI void attn_task(const bf16_t* __restrict__ Qb, const bf16_t* __restrict__ Kh, const bf16_t* __restrict__ Vh, bf16_t* __restrict__ Ob, char* lds, float shiftC) {
;     ...
;   for (int j = 0; j < NT; ++j) {
;     f32x16 p0 = {}, p1 = {};
; #pragma unroll
;     for (int d0 = 0; d0 < 12; ++d0) {
;       const bf16x8 b0 = *(const bf16x8*)(Kr0 + (d0 >> 2) * 128 + kx[d0 & 3]);
;       const bf16x8 b1 = *(const bf16x8*)(Kr0 + 32 * 384 + (d0 >> 2) * 128 + kx[d0 & 3]);
;       p0 = __builtin_amdgcn_mfma_f32_32x32x16_bf16(b0, qr[d0], p0, 0, 0, 0);
;       p1 = __builtin_amdgcn_mfma_f32_32x32x16_bf16(b1, qr[d0], p1, 0, 0, 0);
;     }
;     ABAR();
;     if (j + 1 < NT) KISSUE((j + 1) * 64);
;     float mn, alpha = 1.f;
;     if constexpr (FIXED) {
; #pragma unroll
;       for (int r = 0; r < 16; ++r) p0[r] = __builtin_amdgcn_exp2f(p0[r]);
; #pragma unroll
;       for (int r = 0; r < 16; ++r) p1[r] = __builtin_amdgcn_exp2f(p1[r]);
;     } else partialSM(p0, p1, m_reg, mn, alpha);
	s_waitcnt lgkmcnt(5)
	v_mfma_f32_32x32x16_bf16 v[66:81], v[186:189], v[142:145], 0
	ds_read_b128 v[186:189], v179 offset:128
	v_exp_f32_e32 v210, v210
	v_exp_f32_e32 v211, v211
	v_exp_f32_e32 v212, v212
	v_exp_f32_e32 v213, v213
	s_waitcnt lgkmcnt(5)
	v_mfma_f32_32x32x16_bf16 v[66:81], v[190:193], v[138:141], v[66:81]
	ds_read_b128 v[190:193], v178 offset:128
	v_exp_f32_e32 v214, v214
	v_add_f32_e32 v182, 0, v210
	v_exp_f32_e32 v215, v215
	v_add_f32_e32 v182, v211, v182
	s_waitcnt lgkmcnt(5)
	v_mfma_f32_32x32x16_bf16 v[66:81], v[194:197], v[134:137], v[66:81]
	ds_read_b128 v[194:197], v181 offset:256
	v_exp_f32_e32 v216, v216
	v_add_f32_e32 v182, v212, v182
	v_exp_f32_e32 v217, v217
	v_add_f32_e32 v182, v213, v182
	s_waitcnt lgkmcnt(5)
	v_mfma_f32_32x32x16_bf16 v[66:81], v[198:201], v[126:129], v[66:81]
	ds_read_b128 v[198:201], v180 offset:256
	v_exp_f32_e32 v218, v218
	v_add_f32_e32 v182, v214, v182
	v_exp_f32_e32 v219, v219
	v_add_f32_e32 v182, v215, v182
	s_waitcnt lgkmcnt(5)
	v_mfma_f32_32x32x16_bf16 v[66:81], v[202:205], v[130:133], v[66:81]
	ds_read_b128 v[202:205], v179 offset:256
	v_exp_f32_e32 v220, v220
	v_add_f32_e32 v182, v216, v182
	v_exp_f32_e32 v221, v221
	v_add_f32_e32 v182, v217, v182
	s_waitcnt lgkmcnt(5)
	v_mfma_f32_32x32x16_bf16 v[66:81], v[206:209], v[118:121], v[66:81]
	ds_read_b128 v[206:209], v178 offset:256
	v_exp_f32_e32 v222, v222
	v_add_f32_e32 v182, v218, v182
	v_exp_f32_e32 v223, v223
	v_add_f32_e32 v182, v219, v182
	s_waitcnt lgkmcnt(5)
	v_mfma_f32_32x32x16_bf16 v[66:81], v[186:189], v[122:125], v[66:81]
	ds_read_b128 v[186:189], v181 offset:12288
	v_exp_f32_e32 v224, v224
	v_add_f32_e32 v182, v220, v182
	v_exp_f32_e32 v225, v225
	v_add_f32_e32 v182, v221, v182
	s_waitcnt lgkmcnt(5)
	v_mfma_f32_32x32x16_bf16 v[66:81], v[190:193], v[110:113], v[66:81]
	ds_read_b128 v[190:193], v180 offset:12288
	v_add_f32_e32 v182, v222, v182
	v_add_f32_e32 v182, v223, v182
	v_add_f32_e32 v182, v224, v182
	v_add_f32_e32 v182, v225, v182
	s_waitcnt lgkmcnt(5)
	v_mfma_f32_32x32x16_bf16 v[66:81], v[194:197], v[114:117], v[66:81]
	ds_read_b128 v[194:197], v179 offset:12288
	v_cvt_pk_bf16_f32 v210, v210, v211
	v_cvt_pk_bf16_f32 v211, v212, v213
	v_cvt_pk_bf16_f32 v212, v214, v215
	v_cvt_pk_bf16_f32 v213, v216, v217
	s_waitcnt lgkmcnt(5)
	v_mfma_f32_32x32x16_bf16 v[66:81], v[198:201], v[106:109], v[66:81]
	ds_read_b128 v[198:201], v178 offset:12288
	v_cvt_pk_bf16_f32 v214, v218, v219
	v_cvt_pk_bf16_f32 v215, v220, v221
	v_cvt_pk_bf16_f32 v216, v222, v223
	v_cvt_pk_bf16_f32 v217, v224, v225
	s_waitcnt lgkmcnt(5)
	v_mfma_f32_32x32x16_bf16 v[66:81], v[202:205], v[102:105], v[66:81]
	ds_read_b128 v[202:205], v181 offset:12416
	v_permlane32_swap_b32_e32 v210, v212
	v_permlane32_swap_b32_e32 v211, v213
	v_exp_f32_e32 v226, v226
	v_exp_f32_e32 v227, v227
	s_waitcnt lgkmcnt(5)
	v_mfma_f32_32x32x16_bf16 v[66:81], v[206:209], v[98:101], v[66:81]
	ds_read_b128 v[206:209], v180 offset:12416
	v_exp_f32_e32 v228, v228
	v_permlane32_swap_b32_e32 v214, v216
	v_permlane32_swap_b32_e32 v215, v217
	v_exp_f32_e32 v229, v229
	s_waitcnt lgkmcnt(5)
	v_mfma_f32_32x32x16_bf16 v[82:97], v[186:189], v[142:145], 0
	ds_read_b128 v[186:189], v179 offset:12416
	v_exp_f32_e32 v230, v230
	v_add_f32_e32 v182, v226, v182
	v_exp_f32_e32 v231, v231
	v_add_f32_e32 v182, v227, v182
	s_waitcnt lgkmcnt(5)
	v_mfma_f32_32x32x16_bf16 v[82:97], v[190:193], v[138:141], v[82:97]
	ds_read_b128 v[190:193], v178 offset:12416
	v_exp_f32_e32 v232, v232
	v_add_f32_e32 v182, v228, v182
	v_exp_f32_e32 v233, v233
	v_add_f32_e32 v182, v229, v182
	s_waitcnt lgkmcnt(5)
	v_mfma_f32_32x32x16_bf16 v[82:97], v[194:197], v[134:137], v[82:97]
	ds_read_b128 v[194:197], v181 offset:12544
	v_exp_f32_e32 v234, v234
	v_add_f32_e32 v182, v230, v182
	v_exp_f32_e32 v235, v235
	v_add_f32_e32 v182, v231, v182
	s_waitcnt lgkmcnt(5)
	v_mfma_f32_32x32x16_bf16 v[82:97], v[198:201], v[126:129], v[82:97]
	ds_read_b128 v[198:201], v180 offset:12544
	v_exp_f32_e32 v236, v236
	v_add_f32_e32 v182, v232, v182
	v_exp_f32_e32 v237, v237
	v_add_f32_e32 v182, v233, v182
	s_waitcnt lgkmcnt(5)
	v_mfma_f32_32x32x16_bf16 v[82:97], v[202:205], v[130:133], v[82:97]
	ds_read_b128 v[202:205], v179 offset:12544
	v_exp_f32_e32 v238, v238
	v_add_f32_e32 v182, v234, v182
	v_exp_f32_e32 v239, v239
	v_add_f32_e32 v182, v235, v182
	s_waitcnt lgkmcnt(5)
	v_mfma_f32_32x32x16_bf16 v[82:97], v[206:209], v[118:121], v[82:97]
	ds_read_b128 v[206:209], v178 offset:12544
	v_exp_f32_e32 v240, v240
	v_add_f32_e32 v182, v236, v182
	v_exp_f32_e32 v241, v241
	v_add_f32_e32 v182, v237, v182
	s_waitcnt lgkmcnt(5)
	v_mfma_f32_32x32x16_bf16 v[82:97], v[186:189], v[122:125], v[82:97]
	s_waitcnt vmcnt(0) lgkmcnt(0)
	s_barrier
; DEVI void finishSM(f32x16& p0, f32x16& p1, float alpha, float& l_reg, bf16x8& pa0, bf16x8& pa1, bf16x8& pa2, bf16x8& pa3) {
;   float ps = 0;
; #pragma unroll
;   for (int r = 0; r < 16; ++r) ps += p0[r];
; #pragma unroll
;   for (int r = 0; r < 16; ++r) ps += p1[r];
;   { auto rr = __builtin_amdgcn_permlane32_swap(__float_as_uint(ps), __float_as_uint(ps), false, false);
;     ps = __uint_as_float(rr[0]) + __uint_as_float(rr[1]); }
;   l_reg = l_reg * alpha + ps;
;     ...
;   PK4(p0, 0, pa0); PK4(p0, 8, pa1); PK4(p1, 0, pa2); PK4(p1, 8, pa3);
;     ...
; }
; DEVI int v_st(int k) { const int kk = (k & ~0xC) | ((k & 4) << 1) | ((k & 8) >> 1); return ((kk >> 3) * 4) * 512 + ((kk & 7) * 32) * 2; }
; template <bool FIXED>
; DEVI void attn_task(const bf16_t* __restrict__ Qb, const bf16_t* __restrict__ Kh, const bf16_t* __restrict__ Vh, bf16_t* __restrict__ Ob, char* lds, float shiftC) {
;     ...
;   for (int j = 0; j < NT; ++j) {
;     f32x16 p0 = {}, p1 = {};
; #pragma unroll
;     for (int d0 = 0; d0 < 12; ++d0) {
;       const bf16x8 b0 = *(const bf16x8*)(Kr0 + (d0 >> 2) * 128 + kx[d0 & 3]);
;       const bf16x8 b1 = *(const bf16x8*)(Kr0 + 32 * 384 + (d0 >> 2) * 128 + kx[d0 & 3]);
;       p0 = __builtin_amdgcn_mfma_f32_32x32x16_bf16(b0, qr[d0], p0, 0, 0, 0);
;       p1 = __builtin_amdgcn_mfma_f32_32x32x16_bf16(b1, qr[d0], p1, 0, 0, 0);
;     }
;     ABAR();
;     if (j + 1 < NT) KISSUE((j + 1) * 64);
;     float mn, alpha = 1.f;
;     if constexpr (FIXED) {
; #pragma unroll
;       for (int r = 0; r < 16; ++r) p0[r] = __builtin_amdgcn_exp2f(p0[r]);
; #pragma unroll
;       for (int r = 0; r < 16; ++r) p1[r] = __builtin_amdgcn_exp2f(p1[r]);
;     } else partialSM(p0, p1, m_reg, mn, alpha);
;     if (!FIXED && __any(alpha < 1.f)) {
;       if (hi == 0) al_l[r32] = alpha;
;       asm volatile("s_waitcnt lgkmcnt(0)" ::: "memory");
; #pragma unroll
;       for (int r = 0; r < 16; ++r) { const float a = al_l[crow(r, hi)];
; #pragma unroll
;         for (int d = 0; d < 4; ++d) o[d][r] *= a; }
;     }
;     bf16x8 pa0, pa1, pa2, pa3;
;     finishSM(p0, p1, alpha, l_reg, pa0, pa1, pa2, pa3);
;     pv_one<0>(o[0], vb0, pa0, pa1, pa2, pa3); pv_one<1>(o[1], vb0, pa0, pa1, pa2, pa3);
;     pv_one<2>(o[2], vb0, pa0, pa1, pa2, pa3); pv_one<3>(o[3], vb0, pa0, pa1, pa2, pa3);
;     ABAR();
;     if (j + 1 < NT) VISSUE((j + 1) * 64);
;   }
	s_mov_b32 m0, s26
	s_nop 0
	global_load_lds_dwordx4 v152, s[98:99]
	global_load_lds_dwordx4 v154, s[98:99] offset:1024
	global_load_lds_dwordx4 v156, s[98:99] offset:2048
	global_load_lds_dwordx4 v158, s[98:99] offset:3072
	s_mov_b32 m0, s56
	s_nop 0
	global_load_lds_dwordx4 v160, s[98:99]
	global_load_lds_dwordx4 v162, s[98:99] offset:1024
	s_add_u32 s98, s98, 0x6000
	s_addc_u32 s99, s99, 0
	v_add_f32_e32 v182, v238, v182
	v_add_f32_e32 v182, v239, v182
	v_add_f32_e32 v182, v240, v182
	ds_read_b64_tr_b16 v[186:187], v176 offset:4096
	ds_read_b64_tr_b16 v[188:189], v176 offset:6144
	v_mfma_f32_32x32x16_bf16 v[82:97], v[190:193], v[110:113], v[82:97]
	v_add_f32_e32 v182, v241, v182
	v_cvt_pk_bf16_f32 v218, v226, v227
	v_cvt_pk_bf16_f32 v219, v228, v229
	ds_read_b64_tr_b16 v[190:191], v176 offset:4608
	ds_read_b64_tr_b16 v[192:193], v176 offset:6656
	v_mfma_f32_32x32x16_bf16 v[82:97], v[194:197], v[114:117], v[82:97]
	v_cvt_pk_bf16_f32 v220, v230, v231
	v_cvt_pk_bf16_f32 v221, v232, v233
	v_cvt_pk_bf16_f32 v222, v234, v235
	ds_read_b64_tr_b16 v[194:195], v176 offset:0
	ds_read_b64_tr_b16 v[196:197], v176 offset:2048
	v_mfma_f32_32x32x16_bf16 v[82:97], v[198:201], v[106:109], v[82:97]
	v_cvt_pk_bf16_f32 v223, v236, v237
	v_cvt_pk_bf16_f32 v224, v238, v239
	v_cvt_pk_bf16_f32 v225, v240, v241
	ds_read_b64_tr_b16 v[198:199], v176 offset:512
	ds_read_b64_tr_b16 v[200:201], v176 offset:2560
	v_mfma_f32_32x32x16_bf16 v[82:97], v[202:205], v[102:105], v[82:97]
	v_add_f32_e32 v0, v0, v182
	v_permlane32_swap_b32_e32 v218, v220
	v_permlane32_swap_b32_e32 v219, v221
	ds_read_b64_tr_b16 v[202:203], v176 offset:1024
	ds_read_b64_tr_b16 v[204:205], v176 offset:3072
	v_mfma_f32_32x32x16_bf16 v[82:97], v[206:209], v[98:101], v[82:97]
	v_permlane32_swap_b32_e32 v222, v224
	v_permlane32_swap_b32_e32 v223, v225
	ds_read_b64_tr_b16 v[206:207], v176 offset:1536
	ds_read_b64_tr_b16 v[208:209], v176 offset:3584
	s_waitcnt lgkmcnt(6)
	v_mfma_f32_32x32x16_bf16 v[50:65], v[210:213], v[194:197], v[50:65]
	ds_read_b64_tr_b16 v[194:195], v176 offset:5120
	ds_read_b64_tr_b16 v[196:197], v176 offset:7168
	s_waitcnt lgkmcnt(6)
	v_mfma_f32_32x32x16_bf16 v[34:49], v[210:213], v[198:201], v[34:49]
	ds_read_b64_tr_b16 v[198:199], v176 offset:5632
	ds_read_b64_tr_b16 v[200:201], v176 offset:7680
	s_waitcnt lgkmcnt(6)
	v_mfma_f32_32x32x16_bf16 v[18:33], v[210:213], v[202:205], v[18:33]
	ds_read_b64_tr_b16 v[202:203], v176 offset:8192
	ds_read_b64_tr_b16 v[204:205], v176 offset:10240
	s_waitcnt lgkmcnt(6)
	v_mfma_f32_32x32x16_bf16 v[2:17], v[210:213], v[206:209], v[2:17]
	ds_read_b64_tr_b16 v[206:207], v176 offset:8704
	ds_read_b64_tr_b16 v[208:209], v176 offset:10752
	v_mfma_f32_32x32x16_bf16 v[50:65], v[214:217], v[186:189], v[50:65]
	ds_read_b64_tr_b16 v[186:187], v176 offset:9216
	ds_read_b64_tr_b16 v[188:189], v176 offset:11264
	v_mfma_f32_32x32x16_bf16 v[34:49], v[214:217], v[190:193], v[34:49]
	ds_read_b64_tr_b16 v[190:191], v176 offset:9728
	ds_read_b64_tr_b16 v[192:193], v176 offset:11776
	s_waitcnt lgkmcnt(10)
	v_mfma_f32_32x32x16_bf16 v[18:33], v[214:217], v[194:197], v[18:33]
	ds_read_b64_tr_b16 v[194:195], v176 offset:12288
	ds_read_b64_tr_b16 v[196:197], v176 offset:14336
	s_waitcnt lgkmcnt(10)
	v_mfma_f32_32x32x16_bf16 v[2:17], v[214:217], v[198:201], v[2:17]
	ds_read_b64_tr_b16 v[198:199], v176 offset:12800
	ds_read_b64_tr_b16 v[200:201], v176 offset:14848
	s_waitcnt lgkmcnt(10)
	v_mfma_f32_32x32x16_bf16 v[50:65], v[218:221], v[202:205], v[50:65]
	ds_read_b64_tr_b16 v[202:203], v176 offset:13312
	ds_read_b64_tr_b16 v[204:205], v176 offset:15360
	s_waitcnt lgkmcnt(10)
	v_mfma_f32_32x32x16_bf16 v[34:49], v[218:221], v[206:209], v[34:49]
	ds_read_b64_tr_b16 v[206:207], v176 offset:13824
	ds_read_b64_tr_b16 v[208:209], v176 offset:15872
	s_waitcnt lgkmcnt(10)
	v_mfma_f32_32x32x16_bf16 v[18:33], v[218:221], v[186:189], v[18:33]
	s_waitcnt lgkmcnt(8)
	v_mfma_f32_32x32x16_bf16 v[2:17], v[218:221], v[190:193], v[2:17]
	s_waitcnt lgkmcnt(6)
	v_mfma_f32_32x32x16_bf16 v[50:65], v[222:225], v[194:197], v[50:65]
	s_waitcnt vmcnt(0) lgkmcnt(0)
	s_barrier
	s_mov_b32 m0, s58
	ds_read_b128 v[186:189], v181
	global_load_lds_dwordx4 v242, s[100:101]
	global_load_lds_dwordx4 v150, s[100:101] offset:1024
	global_load_lds_dwordx4 v243, s[100:101] offset:2048
	global_load_lds_dwordx4 v146, s[100:101] offset:3072
	s_add_u32 s100, s100, 0x4000
	s_addc_u32 s101, s101, 0
	ds_read_b128 v[190:193], v180
	ds_read_b128 v[194:197], v179
	v_mfma_f32_32x32x16_bf16 v[34:49], v[222:225], v[198:201], v[34:49]
	ds_read_b128 v[198:201], v178
	v_mfma_f32_32x32x16_bf16 v[18:33], v[222:225], v[202:205], v[18:33]
	ds_read_b128 v[202:205], v181 offset:128
	v_mfma_f32_32x32x16_bf16 v[2:17], v[222:225], v[206:209], v[2:17]
	ds_read_b128 v[206:209], v180 offset:128
	s_add_i32 s62, s62, -1
	s_branch .Lat7_top
; #define KISSUE(k0) do { const char* kp_ = Kc + (size_t)(k0) * 384; _Pragma("unroll") for (int e = 0; e < 6; ++e) \
;       __builtin_amdgcn_global_load_lds((const unsigned*)(kp_ + ksrc[e]), (unsigned*)(K_lds + (wu * 6 + e) * 1024), 16, 0, 0); } while (0)
; #define ABAR() do { asm volatile("s_waitcnt vmcnt(0) lgkmcnt(0)" ::: "memory"); __builtin_amdgcn_s_barrier(); } while (0)
; DEVI void finishSM(f32x16& p0, f32x16& p1, float alpha, float& l_reg, bf16x8& pa0, bf16x8& pa1, bf16x8& pa2, bf16x8& pa3) {
;   float ps = 0;
; #pragma unroll
;   for (int r = 0; r < 16; ++r) ps += p0[r];
; #pragma unroll
;   for (int r = 0; r < 16; ++r) ps += p1[r];
;   { auto rr = __builtin_amdgcn_permlane32_swap(__float_as_uint(ps), __float_as_uint(ps), false, false);
;     ps = __uint_as_float(rr[0]) + __uint_as_float(rr[1]); }
;   l_reg = l_reg * alpha + ps;
;     ...
;   PK4(p0, 0, pa0); PK4(p0, 8, pa1); PK4(p1, 0, pa2); PK4(p1, 8, pa3);
; template <bool FIXED>
; DEVI void attn_task(const bf16_t* __restrict__ Qb, const bf16_t* __restrict__ Kh, const bf16_t* __restrict__ Vh, bf16_t* __restrict__ Ob, char* lds, float shiftC) {
;     ...
;   for (int j = 0; j < NT; ++j) {
;     f32x16 p0 = {}, p1 = {};
; #pragma unroll
;     for (int d0 = 0; d0 < 12; ++d0) {
;       const bf16x8 b0 = *(const bf16x8*)(Kr0 + (d0 >> 2) * 128 + kx[d0 & 3]);
;       const bf16x8 b1 = *(const bf16x8*)(Kr0 + 32 * 384 + (d0 >> 2) * 128 + kx[d0 & 3]);
;       p0 = __builtin_amdgcn_mfma_f32_32x32x16_bf16(b0, qr[d0], p0, 0, 0, 0);
;       p1 = __builtin_amdgcn_mfma_f32_32x32x16_bf16(b1, qr[d0], p1, 0, 0, 0);
;     }
;     ABAR();
;     if (j + 1 < NT) KISSUE((j + 1) * 64);
;     float mn, alpha = 1.f;
;     if constexpr (FIXED) {
; #pragma unroll
;       for (int r = 0; r < 16; ++r) p0[r] = __builtin_amdgcn_exp2f(p0[r]);
; #pragma unroll
;       for (int r = 0; r < 16; ++r) p1[r] = __builtin_amdgcn_exp2f(p1[r]);
;     } else partialSM(p0, p1, m_reg, mn, alpha);
.Lat7_done:
	v_mov_b32_e32 v183, v0
	s_nop 1
	v_permlane32_swap_b32_e32 v0, v183
	v_add_f32_e32 v0, v0, v183
	ds_read_b128 v[66:69], v181
	ds_read_b128 v[146:149], v181 offset:128
	ds_read_b128 v[82:85], v181 offset:12288
	ds_read_b128 v[150:153], v181 offset:256
	s_waitcnt lgkmcnt(0)
	v_mfma_f32_32x32x16_bf16 v[66:81], v[66:69], v[142:145], 0
	v_mfma_f32_32x32x16_bf16 v[82:97], v[82:85], v[142:145], 0
	ds_read_b128 v[142:145], v180
	ds_read_b128 v[154:157], v180 offset:128
	s_waitcnt lgkmcnt(0)
	v_mfma_f32_32x32x16_bf16 v[66:81], v[142:145], v[138:141], v[66:81]
	ds_read_b128 v[142:145], v180 offset:12288
	ds_read_b128 v[158:161], v180 offset:256
	s_waitcnt lgkmcnt(0)
	v_mfma_f32_32x32x16_bf16 v[82:97], v[142:145], v[138:141], v[82:97]
	ds_read_b128 v[138:141], v179
	ds_read_b128 v[142:145], v179 offset:128
	s_waitcnt lgkmcnt(0)
	v_mfma_f32_32x32x16_bf16 v[66:81], v[138:141], v[134:137], v[66:81]
	ds_read_b128 v[138:141], v179 offset:12288
	ds_read_b128 v[182:185], v179 offset:256
	s_waitcnt lgkmcnt(0)
	v_mfma_f32_32x32x16_bf16 v[82:97], v[138:141], v[134:137], v[82:97]
	ds_read_b128 v[134:137], v178
	ds_read_b128 v[138:141], v178 offset:128
	s_waitcnt lgkmcnt(0)
	v_mfma_f32_32x32x16_bf16 v[66:81], v[134:137], v[126:129], v[66:81]
	ds_read_b128 v[134:137], v178 offset:12288
	ds_read_b128 v[186:189], v178 offset:256
	v_mfma_f32_32x32x16_bf16 v[66:81], v[146:149], v[130:133], v[66:81]
	s_waitcnt lgkmcnt(0)
	v_mfma_f32_32x32x16_bf16 v[82:97], v[134:137], v[126:129], v[82:97]
	ds_read_b128 v[126:129], v181 offset:12416
	ds_read_b128 v[134:137], v181 offset:12544
	v_mfma_f32_32x32x16_bf16 v[66:81], v[154:157], v[118:121], v[66:81]
	s_waitcnt lgkmcnt(0)
	v_mfma_f32_32x32x16_bf16 v[82:97], v[126:129], v[130:133], v[82:97]
	ds_read_b128 v[126:129], v180 offset:12416
	ds_read_b128 v[130:133], v180 offset:12544
	v_mfma_f32_32x32x16_bf16 v[66:81], v[142:145], v[122:125], v[66:81]
	s_waitcnt lgkmcnt(0)
	v_mfma_f32_32x32x16_bf16 v[82:97], v[126:129], v[118:121], v[82:97]
	ds_read_b128 v[118:121], v179 offset:12416
	ds_read_b128 v[126:129], v179 offset:12544
	v_mfma_f32_32x32x16_bf16 v[66:81], v[138:141], v[110:113], v[66:81]
	s_waitcnt lgkmcnt(0)
	v_mfma_f32_32x32x16_bf16 v[82:97], v[118:121], v[122:125], v[82:97]
	ds_read_b128 v[118:121], v178 offset:12416
	ds_read_b128 v[122:125], v178 offset:12544
	s_waitcnt vmcnt(0) lgkmcnt(0)
	s_barrier
	v_mfma_f32_32x32x16_bf16 v[66:81], v[150:153], v[114:117], v[66:81]
	s_waitcnt lgkmcnt(0)
	v_mfma_f32_32x32x16_bf16 v[82:97], v[118:121], v[110:113], v[82:97]
	v_and_b32_e32 v110, 0x3fffffc0, v177
	v_lshl_add_u32 v110, v110, 2, 0
	v_mfma_f32_32x32x16_bf16 v[66:81], v[158:161], v[106:109], v[66:81]
	v_mfma_f32_32x32x16_bf16 v[82:97], v[134:137], v[114:117], v[82:97]
	v_mfma_f32_32x32x16_bf16 v[66:81], v[182:185], v[102:105], v[66:81]
	v_mfma_f32_32x32x16_bf16 v[66:81], v[186:189], v[98:101], v[66:81]
	v_mfma_f32_32x32x16_bf16 v[82:97], v[130:133], v[106:109], v[82:97]
	s_nop 10
	v_exp_f32_e32 v111, v66
	v_exp_f32_e32 v112, v67
	v_exp_f32_e32 v106, v68
	v_exp_f32_e32 v69, v69
	v_exp_f32_e32 v70, v70
	v_add_f32_e32 v66, 0, v111
	v_exp_f32_e32 v71, v71
	v_mfma_f32_32x32x16_bf16 v[82:97], v[126:129], v[102:105], v[82:97]
	v_add_f32_e32 v66, v112, v66
	v_exp_f32_e32 v72, v72
	v_add_f32_e32 v66, v106, v66
	v_exp_f32_e32 v73, v73
	v_add_f32_e32 v66, v69, v66
	v_exp_f32_e32 v74, v74
	v_add_f32_e32 v66, v70, v66
	v_mfma_f32_32x32x16_bf16 v[82:97], v[122:125], v[98:101], v[82:97]
	v_exp_f32_e32 v75, v75
	v_add_f32_e32 v66, v71, v66
	v_exp_f32_e32 v76, v76
	v_add_f32_e32 v66, v72, v66
	v_exp_f32_e32 v77, v77
	v_add_f32_e32 v66, v73, v66
	v_exp_f32_e32 v78, v78
	v_add_f32_e32 v66, v74, v66
	v_exp_f32_e32 v79, v79
	v_add_f32_e32 v66, v75, v66
	v_exp_f32_e32 v80, v80
	v_add_f32_e32 v66, v76, v66
	v_exp_f32_e32 v81, v81
	v_add_f32_e32 v66, v77, v66
	v_exp_f32_e32 v82, v82
	v_add_f32_e32 v66, v78, v66
	v_exp_f32_e32 v83, v83
	v_add_f32_e32 v66, v79, v66
	v_exp_f32_e32 v84, v84
	v_add_f32_e32 v66, v80, v66
	v_exp_f32_e32 v85, v85
	v_add_f32_e32 v66, v81, v66
	v_exp_f32_e32 v86, v86
	v_add_f32_e32 v66, v82, v66
	v_exp_f32_e32 v87, v87
	v_add_f32_e32 v66, v83, v66
	v_exp_f32_e32 v88, v88
	v_add_f32_e32 v66, v84, v66
	v_exp_f32_e32 v89, v89
	v_add_f32_e32 v66, v85, v66
	v_exp_f32_e32 v90, v90
	v_add_f32_e32 v66, v86, v66
	v_exp_f32_e32 v91, v91
	v_add_f32_e32 v66, v87, v66
	v_exp_f32_e32 v92, v92
	v_add_f32_e32 v66, v88, v66
	v_exp_f32_e32 v93, v93
	v_add_f32_e32 v66, v89, v66
	v_exp_f32_e32 v94, v94
	v_add_f32_e32 v66, v90, v66
	v_exp_f32_e32 v95, v95
	v_add_f32_e32 v66, v91, v66
	v_cvt_pk_bf16_f32 v70, v70, v71
	v_cvt_pk_bf16_f32 v71, v72, v73
	v_cvt_pk_bf16_f32 v73, v76, v77
	v_cvt_pk_bf16_f32 v77, v84, v85
	ds_read_b64_tr_b16 v[84:85], v176 offset:0
	v_exp_f32_e32 v96, v96
	v_add_f32_e32 v66, v92, v66
	v_cvt_pk_bf16_f32 v72, v74, v75
	v_cvt_pk_bf16_f32 v74, v78, v79
	v_cvt_pk_bf16_f32 v78, v86, v87
	ds_read_b64_tr_b16 v[86:87], v176 offset:0x800
	v_exp_f32_e32 v97, v97
	v_add_f32_e32 v66, v93, v66
	v_cvt_pk_bf16_f32 v79, v88, v89
	ds_read_b64_tr_b16 v[88:89], v176 offset:0x1000
	v_add_f32_e32 v66, v94, v66
	v_cvt_pk_bf16_f32 v75, v80, v81
	v_cvt_pk_bf16_f32 v80, v90, v91
	ds_read_b64_tr_b16 v[90:91], v176 offset:0x1800
	v_add_f32_e32 v66, v95, v66
	v_cvt_pk_bf16_f32 v81, v92, v93
	ds_read_b64_tr_b16 v[92:93], v176 offset:0x2000
	v_add_f32_e32 v66, v96, v66
	v_cvt_pk_bf16_f32 v76, v82, v83
	v_cvt_pk_bf16_f32 v82, v94, v95
	ds_read_b64_tr_b16 v[94:95], v176 offset:0x2800
	v_add_f32_e32 v66, v97, v66
	v_cvt_pk_bf16_f32 v83, v96, v97
	ds_read_b64_tr_b16 v[96:97], v176 offset:0x3000
	ds_read_b64_tr_b16 v[98:99], v176 offset:0x3800
	s_waitcnt lgkmcnt(0)
; DEVI bf16_t f2bf(float x) { return (bf16_t)(cvtpk(x, 0.f) & 0xffffu); }
; DEVI int crow(int r, int hi) { return (r & 3) + 8 * (r >> 2) + 4 * hi; }
; #define VISSUE(k0) do { const char* vp_ = Vc + (size_t)(k0) * 256; _Pragma("unroll") for (int e = 0; e < 4; ++e) \
;       __builtin_amdgcn_global_load_lds((const unsigned*)(vp_ + vsrc[e]), (unsigned*)(V_lds + (wu * 4 + e) * 1024), 16, 0, 0); } while (0)
; #define ABAR() do { asm volatile("s_waitcnt vmcnt(0) lgkmcnt(0)" ::: "memory"); __builtin_amdgcn_s_barrier(); } while (0)
; template <bool FIXED>
; DEVI void attn_task(const bf16_t* __restrict__ Qb, const bf16_t* __restrict__ Kh, const bf16_t* __restrict__ Vh, bf16_t* __restrict__ Ob, char* lds, float shiftC) {
;     ...
;     bf16x8 pa0, pa1, pa2, pa3;
;     finishSM(p0, p1, alpha, l_reg, pa0, pa1, pa2, pa3);
;     pv_one<0>(o[0], vb0, pa0, pa1, pa2, pa3); pv_one<1>(o[1], vb0, pa0, pa1, pa2, pa3);
;     pv_one<2>(o[2], vb0, pa0, pa1, pa2, pa3); pv_one<3>(o[3], vb0, pa0, pa1, pa2, pa3);
;     ABAR();
;     if (j + 1 < NT) VISSUE((j + 1) * 64);
;   }
;     ...
;   if (hi == 0) li_l[r32] = l_reg;
;   asm volatile("s_waitcnt lgkmcnt(0)" ::: "memory");
;   char* Oc = (char*)Ob;
; #pragma unroll
;   for (int r = 0; r < 16; ++r) {
;     const int orow = crow(r, hi);
;     const float rl = 1.f / li_l[orow];
;     const unsigned ooff = (unsigned)((wid * 32 + orow) * LDP + r32) * 2u;
; #pragma unroll
;     for (int d0 = 0; d0 < 4; ++d0) *(bf16_t*)(Oc + (ooff + d0 * 64)) = f2bf(o[d0][r] * rl);
;   }
	v_mov_b32_e32 v67, v66
	s_nop 1
	v_permlane32_swap_b32_e32 v66, v67
	v_cvt_pk_bf16_f32 v68, v111, v112
	v_cvt_pk_bf16_f32 v69, v106, v69
	v_permlane32_swap_b32_e32 v72, v74
	v_permlane32_swap_b32_e32 v68, v70
	v_permlane32_swap_b32_e32 v69, v71
	v_permlane32_swap_b32_e32 v73, v75
	v_permlane32_swap_b32_e32 v76, v78
	v_permlane32_swap_b32_e32 v77, v79
	v_permlane32_swap_b32_e32 v80, v82
	v_permlane32_swap_b32_e32 v81, v83
	v_mfma_f32_32x32x16_bf16 v[50:65], v[68:71], v[84:87], v[50:65]
	ds_read_b64_tr_b16 v[84:85], v176 offset:0x200
	ds_read_b64_tr_b16 v[86:87], v176 offset:0xa00
	v_mfma_f32_32x32x16_bf16 v[50:65], v[72:75], v[88:91], v[50:65]
	ds_read_b64_tr_b16 v[88:89], v176 offset:0x1200
	ds_read_b64_tr_b16 v[90:91], v176 offset:0x1a00
	v_mfma_f32_32x32x16_bf16 v[50:65], v[76:79], v[92:95], v[50:65]
	ds_read_b64_tr_b16 v[92:93], v176 offset:0x2200
	ds_read_b64_tr_b16 v[94:95], v176 offset:0x2a00
	ds_read_b64_tr_b16 v[100:101], v176 offset:0x3200
	ds_read_b64_tr_b16 v[102:103], v176 offset:0x3a00
	s_waitcnt lgkmcnt(0)
	v_mfma_f32_32x32x16_bf16 v[50:65], v[80:83], v[96:99], v[50:65]
	v_mfma_f32_32x32x16_bf16 v[34:49], v[68:71], v[84:87], v[34:49]
	ds_read_b64_tr_b16 v[84:85], v176 offset:0x400
	ds_read_b64_tr_b16 v[86:87], v176 offset:0xc00
	v_mfma_f32_32x32x16_bf16 v[34:49], v[72:75], v[88:91], v[34:49]
	ds_read_b64_tr_b16 v[88:89], v176 offset:0x1400
	ds_read_b64_tr_b16 v[90:91], v176 offset:0x1c00
	v_mfma_f32_32x32x16_bf16 v[34:49], v[76:79], v[92:95], v[34:49]
	ds_read_b64_tr_b16 v[92:93], v176 offset:0x2400
	ds_read_b64_tr_b16 v[94:95], v176 offset:0x2c00
	ds_read_b64_tr_b16 v[96:97], v176 offset:0x3400
	ds_read_b64_tr_b16 v[98:99], v176 offset:0x3c00
	s_waitcnt lgkmcnt(0)
	v_mfma_f32_32x32x16_bf16 v[34:49], v[80:83], v[100:103], v[34:49]
	v_mfma_f32_32x32x16_bf16 v[18:33], v[68:71], v[84:87], v[18:33]
	ds_read_b64_tr_b16 v[84:85], v176 offset:0x600
	ds_read_b64_tr_b16 v[86:87], v176 offset:0xe00
	v_mfma_f32_32x32x16_bf16 v[18:33], v[72:75], v[88:91], v[18:33]
	ds_read_b64_tr_b16 v[88:89], v176 offset:0x1600
	ds_read_b64_tr_b16 v[90:91], v176 offset:0x1e00
	v_mfma_f32_32x32x16_bf16 v[18:33], v[76:79], v[92:95], v[18:33]
	ds_read_b64_tr_b16 v[92:93], v176 offset:0x2600
	ds_read_b64_tr_b16 v[94:95], v176 offset:0x2e00
	ds_read_b64_tr_b16 v[100:101], v176 offset:0x3600
	ds_read_b64_tr_b16 v[102:103], v176 offset:0x3e00
	s_waitcnt lgkmcnt(0)
	v_mfma_f32_32x32x16_bf16 v[18:33], v[80:83], v[96:99], v[18:33]
	v_mfma_f32_32x32x16_bf16 v[2:17], v[68:71], v[84:87], v[2:17]
	s_waitcnt vmcnt(0) lgkmcnt(0)
	v_cmp_gt_u32_e32 vcc, 32, v175
	s_barrier
	v_mfma_f32_32x32x16_bf16 v[2:17], v[72:75], v[88:91], v[2:17]
	v_mfma_f32_32x32x16_bf16 v[2:17], v[76:79], v[92:95], v[2:17]
	v_mfma_f32_32x32x16_bf16 v[2:17], v[80:83], v[100:103], v[2:17]
	s_and_saveexec_b64 s[26:27], vcc
	v_add_f32_e32 v66, v66, v67
	v_add_f32_e32 v0, v0, v66
	v_lshl_add_u32 v66, v172, 2, v110
	ds_write_b32 v66, v0 offset:40960
	s_or_b64 exec, exec, s[26:27]
	v_lshl_add_u32 v0, v173, 4, v110
	s_waitcnt lgkmcnt(0)
	v_add_u32_e32 v68, 0xa000, v0
	ds_read2_b32 v[70:71], v68 offset1:1
	ds_read2_b32 v[66:67], v68 offset0:2 offset1:3
	ds_read2_b32 v[72:73], v68 offset0:8 offset1:9
	ds_read2_b32 v[74:75], v68 offset0:10 offset1:11
	s_waitcnt lgkmcnt(0)
	v_div_scale_f32 v0, s[26:27], v70, v70, 1.0
	v_rcp_f32_e32 v69, v0
	v_div_scale_f32 v76, vcc, 1.0, v70, 1.0
	v_fma_f32 v77, -v0, v69, 1.0
	v_fmac_f32_e32 v69, v77, v69
	v_mul_f32_e32 v77, v76, v69
	v_fma_f32 v78, -v0, v77, v76
	v_fmac_f32_e32 v77, v78, v69
	v_fma_f32 v0, -v0, v77, v76
	v_div_fmas_f32 v0, v0, v69, v77
	v_div_fixup_f32 v69, v0, v70, 1.0
	v_lshl_or_b32 v0, v173, 2, v174
	v_mul_lo_u32 v70, v0, s47
	v_or_b32_e32 v70, v70, v172
	v_mul_f32_e32 v18, v18, v69
	v_lshlrev_b32_e32 v70, 1, v70
	v_mul_f32_e32 v34, v34, v69
	v_cvt_pk_bf16_f32 v18, v18, v1
	v_cvt_pk_bf16_f32 v34, v34, v1
	global_store_short v70, v18, s[42:43] offset:128
	v_div_scale_f32 v18, s[26:27], v71, v71, 1.0
	global_store_short v70, v34, s[42:43] offset:64
	v_rcp_f32_e32 v34, v18
	v_mul_f32_e32 v2, v2, v69
	v_cvt_pk_bf16_f32 v2, v2, v1
	v_mul_f32_e32 v50, v50, v69
	global_store_short v70, v2, s[42:43] offset:192
	v_fma_f32 v2, -v18, v34, 1.0
	v_cvt_pk_bf16_f32 v50, v50, v1
	v_fmac_f32_e32 v34, v2, v34
	v_div_scale_f32 v2, vcc, 1.0, v71, 1.0
	global_store_short v70, v50, s[42:43]
	v_mul_f32_e32 v50, v2, v34
	v_fma_f32 v69, -v18, v50, v2
	v_fmac_f32_e32 v50, v69, v34
	v_fma_f32 v2, -v18, v50, v2
	v_div_fmas_f32 v2, v2, v34, v50
	v_or_b32_e32 v18, 1, v0
	v_div_fixup_f32 v2, v2, v71, 1.0
	v_mul_lo_u32 v18, v18, s47
	v_or_b32_e32 v18, v18, v172
	v_mul_f32_e32 v34, v51, v2
	v_lshlrev_b32_e32 v18, 1, v18
	v_cvt_pk_bf16_f32 v34, v34, v1
	v_mul_f32_e32 v19, v19, v2
	global_store_short v18, v34, s[42:43]
	v_mul_f32_e32 v34, v35, v2
	v_cvt_pk_bf16_f32 v19, v19, v1
	v_cvt_pk_bf16_f32 v34, v34, v1
	global_store_short v18, v19, s[42:43] offset:128
	v_div_scale_f32 v19, s[26:27], v66, v66, 1.0
	global_store_short v18, v34, s[42:43] offset:64
	v_rcp_f32_e32 v34, v19
	v_mul_f32_e32 v2, v3, v2
	v_cvt_pk_bf16_f32 v2, v2, v1
	global_store_short v18, v2, s[42:43] offset:192
	v_fma_f32 v2, -v19, v34, 1.0
	v_fmac_f32_e32 v34, v2, v34
	v_div_scale_f32 v2, vcc, 1.0, v66, 1.0
	v_mul_f32_e32 v3, v2, v34
	v_fma_f32 v18, -v19, v3, v2
	v_fmac_f32_e32 v3, v18, v34
	v_fma_f32 v2, -v19, v3, v2
	v_div_fmas_f32 v2, v2, v34, v3
	v_or_b32_e32 v3, 2, v0
	v_div_fixup_f32 v2, v2, v66, 1.0
	v_mul_lo_u32 v3, v3, s47
	v_or_b32_e32 v3, v3, v172
	v_mul_f32_e32 v18, v52, v2
	v_lshlrev_b32_e32 v3, 1, v3
	v_cvt_pk_bf16_f32 v18, v18, v1
	global_store_short v3, v18, s[42:43]
	v_mul_f32_e32 v18, v36, v2
; DEVI bf16_t f2bf(float x) { return (bf16_t)(cvtpk(x, 0.f) & 0xffffu); }
; DEVI int crow(int r, int hi) { return (r & 3) + 8 * (r >> 2) + 4 * hi; }
; template <bool FIXED>
; DEVI void attn_task(const bf16_t* __restrict__ Qb, const bf16_t* __restrict__ Kh, const bf16_t* __restrict__ Vh, bf16_t* __restrict__ Ob, char* lds, float shiftC) {
;     ...
; #pragma unroll
;   for (int r = 0; r < 16; ++r) {
;     const int orow = crow(r, hi);
;     const float rl = 1.f / li_l[orow];
;     const unsigned ooff = (unsigned)((wid * 32 + orow) * LDP + r32) * 2u;
; #pragma unroll
;     for (int d0 = 0; d0 < 4; ++d0) *(bf16_t*)(Oc + (ooff + d0 * 64)) = f2bf(o[d0][r] * rl);
;   }
	v_cvt_pk_bf16_f32 v18, v18, v1
	global_store_short v3, v18, s[42:43] offset:64
	v_mul_f32_e32 v18, v20, v2
	v_cvt_pk_bf16_f32 v18, v18, v1
	global_store_short v3, v18, s[42:43] offset:128
	v_div_scale_f32 v18, s[26:27], v67, v67, 1.0
	v_rcp_f32_e32 v19, v18
	v_mul_f32_e32 v2, v4, v2
	v_cvt_pk_bf16_f32 v2, v2, v1
	global_store_short v3, v2, s[42:43] offset:192
	v_fma_f32 v2, -v18, v19, 1.0
	v_fmac_f32_e32 v19, v2, v19
	v_div_scale_f32 v2, vcc, 1.0, v67, 1.0
	v_mul_f32_e32 v3, v2, v19
	v_fma_f32 v4, -v18, v3, v2
	v_fmac_f32_e32 v3, v4, v19
	v_fma_f32 v2, -v18, v3, v2
	v_div_fmas_f32 v2, v2, v19, v3
	v_or_b32_e32 v3, 3, v0
	v_div_fixup_f32 v2, v2, v67, 1.0
	v_mul_lo_u32 v3, v3, s47
	v_or_b32_e32 v3, v3, v172
	v_mul_f32_e32 v4, v53, v2
	v_lshlrev_b32_e32 v3, 1, v3
	v_cvt_pk_bf16_f32 v4, v4, v1
	global_store_short v3, v4, s[42:43]
	v_mul_f32_e32 v4, v37, v2
	v_cvt_pk_bf16_f32 v4, v4, v1
	global_store_short v3, v4, s[42:43] offset:64
	v_mul_f32_e32 v4, v21, v2
	v_cvt_pk_bf16_f32 v4, v4, v1
	v_add_u32_e32 v18, 0x80, v3
	global_store_short v18, v4, s[42:43]
	v_div_scale_f32 v4, s[26:27], v72, v72, 1.0
	v_mul_f32_e32 v2, v5, v2
	v_rcp_f32_e32 v5, v4
	v_cvt_pk_bf16_f32 v2, v2, v1
	v_add_u32_e32 v3, 0xc0, v3
	global_store_short v3, v2, s[42:43]
	v_fma_f32 v2, -v4, v5, 1.0
	v_fmac_f32_e32 v5, v2, v5
	v_div_scale_f32 v2, vcc, 1.0, v72, 1.0
	v_mul_f32_e32 v3, v2, v5
	v_fma_f32 v18, -v4, v3, v2
	v_fmac_f32_e32 v3, v18, v5
	v_fma_f32 v2, -v4, v3, v2
	v_div_fmas_f32 v2, v2, v5, v3
	v_or_b32_e32 v3, 8, v0
	v_div_fixup_f32 v2, v2, v72, 1.0
	v_mul_lo_u32 v3, v3, s47
	v_or_b32_e32 v3, v3, v172
	v_mul_f32_e32 v4, v54, v2
	v_lshlrev_b32_e32 v3, 1, v3
	v_cvt_pk_bf16_f32 v4, v4, v1
	global_store_short v3, v4, s[42:43]
	v_mul_f32_e32 v4, v38, v2
	v_cvt_pk_bf16_f32 v4, v4, v1
	global_store_short v3, v4, s[42:43] offset:64
	v_mul_f32_e32 v4, v22, v2
	v_cvt_pk_bf16_f32 v4, v4, v1
	global_store_short v3, v4, s[42:43] offset:128
	v_div_scale_f32 v4, s[26:27], v73, v73, 1.0
	v_rcp_f32_e32 v5, v4
	v_mul_f32_e32 v2, v6, v2
	v_cvt_pk_bf16_f32 v2, v2, v1
	global_store_short v3, v2, s[42:43] offset:192
	v_fma_f32 v2, -v4, v5, 1.0
	v_fmac_f32_e32 v5, v2, v5
	v_div_scale_f32 v2, vcc, 1.0, v73, 1.0
	v_mul_f32_e32 v3, v2, v5
	v_fma_f32 v6, -v4, v3, v2
	v_fmac_f32_e32 v3, v6, v5
	v_fma_f32 v2, -v4, v3, v2
	v_div_fmas_f32 v2, v2, v5, v3
	v_or_b32_e32 v3, 9, v0
	v_div_fixup_f32 v2, v2, v73, 1.0
	v_mul_lo_u32 v3, v3, s47
	v_or_b32_e32 v3, v3, v172
	v_mul_f32_e32 v4, v55, v2
	v_lshlrev_b32_e32 v3, 1, v3
	v_cvt_pk_bf16_f32 v4, v4, v1
	global_store_short v3, v4, s[42:43]
	v_mul_f32_e32 v4, v39, v2
	v_cvt_pk_bf16_f32 v4, v4, v1
	global_store_short v3, v4, s[42:43] offset:64
	v_mul_f32_e32 v4, v23, v2
	v_cvt_pk_bf16_f32 v4, v4, v1
	global_store_short v3, v4, s[42:43] offset:128
	v_div_scale_f32 v4, s[26:27], v74, v74, 1.0
	v_rcp_f32_e32 v5, v4
	v_mul_f32_e32 v2, v7, v2
	v_cvt_pk_bf16_f32 v2, v2, v1
	global_store_short v3, v2, s[42:43] offset:192
	v_fma_f32 v2, -v4, v5, 1.0
	v_fmac_f32_e32 v5, v2, v5
	v_div_scale_f32 v2, vcc, 1.0, v74, 1.0
	v_mul_f32_e32 v3, v2, v5
	v_fma_f32 v6, -v4, v3, v2
	v_fmac_f32_e32 v3, v6, v5
	v_fma_f32 v2, -v4, v3, v2
	v_div_fmas_f32 v2, v2, v5, v3
	v_or_b32_e32 v3, 10, v0
	v_div_fixup_f32 v2, v2, v74, 1.0
	v_mul_lo_u32 v3, v3, s47
	v_or_b32_e32 v3, v3, v172
	v_mul_f32_e32 v4, v56, v2
	v_lshlrev_b32_e32 v3, 1, v3
	v_cvt_pk_bf16_f32 v4, v4, v1
	global_store_short v3, v4, s[42:43]
	v_mul_f32_e32 v4, v40, v2
	v_cvt_pk_bf16_f32 v4, v4, v1
	global_store_short v3, v4, s[42:43] offset:64
	v_mul_f32_e32 v4, v24, v2
	v_cvt_pk_bf16_f32 v4, v4, v1
	global_store_short v3, v4, s[42:43] offset:128
	v_div_scale_f32 v4, s[26:27], v75, v75, 1.0
	v_rcp_f32_e32 v5, v4
	v_mul_f32_e32 v2, v8, v2
	v_cvt_pk_bf16_f32 v2, v2, v1
	global_store_short v3, v2, s[42:43] offset:192
	v_fma_f32 v2, -v4, v5, 1.0
	v_fmac_f32_e32 v5, v2, v5
	v_div_scale_f32 v2, vcc, 1.0, v75, 1.0
	v_mul_f32_e32 v3, v2, v5
	v_fma_f32 v6, -v4, v3, v2
	v_fmac_f32_e32 v3, v6, v5
	v_fma_f32 v2, -v4, v3, v2
	v_div_fmas_f32 v2, v2, v5, v3
	v_or_b32_e32 v3, 11, v0
	v_mul_lo_u32 v3, v3, s47
	v_div_fixup_f32 v2, v2, v75, 1.0
	v_or_b32_e32 v3, v3, v172
	v_lshlrev_b32_e32 v18, 1, v3
	v_mul_f32_e32 v3, v57, v2
	v_cvt_pk_bf16_f32 v3, v3, v1
	global_store_short v18, v3, s[42:43]
	v_mul_f32_e32 v3, v41, v2
	v_cvt_pk_bf16_f32 v3, v3, v1
	global_store_short v18, v3, s[42:43] offset:64
	v_mul_f32_e32 v3, v25, v2
	v_add_u32_e32 v4, 0x80, v18
	v_cvt_pk_bf16_f32 v3, v3, v1
	global_store_short v4, v3, s[42:43]
	v_mul_f32_e32 v19, v9, v2
	ds_read2_b32 v[2:3], v68 offset0:16 offset1:17
	ds_read2_b32 v[4:5], v68 offset0:18 offset1:19
	ds_read2_b32 v[6:7], v68 offset0:24 offset1:25
	ds_read2_b32 v[8:9], v68 offset0:26 offset1:27
	v_add_u32_e32 v18, 0xc0, v18
	s_waitcnt lgkmcnt(0)
; DEVI bf16_t f2bf(float x) { return (bf16_t)(cvtpk(x, 0.f) & 0xffffu); }
; DEVI int crow(int r, int hi) { return (r & 3) + 8 * (r >> 2) + 4 * hi; }
; template <bool FIXED>
; DEVI void attn_task(const bf16_t* __restrict__ Qb, const bf16_t* __restrict__ Kh, const bf16_t* __restrict__ Vh, bf16_t* __restrict__ Ob, char* lds, float shiftC) {
;     ...
; #pragma unroll
;   for (int r = 0; r < 16; ++r) {
;     const int orow = crow(r, hi);
;     const float rl = 1.f / li_l[orow];
;     const unsigned ooff = (unsigned)((wid * 32 + orow) * LDP + r32) * 2u;
; #pragma unroll
;     for (int d0 = 0; d0 < 4; ++d0) *(bf16_t*)(Oc + (ooff + d0 * 64)) = f2bf(o[d0][r] * rl);
;   }
	v_div_scale_f32 v20, s[26:27], v2, v2, 1.0
	v_rcp_f32_e32 v21, v20
	v_cvt_pk_bf16_f32 v19, v19, v1
	global_store_short v18, v19, s[42:43]
	v_fma_f32 v18, -v20, v21, 1.0
	v_fmac_f32_e32 v21, v18, v21
	v_div_scale_f32 v18, vcc, 1.0, v2, 1.0
	v_mul_f32_e32 v19, v18, v21
	v_fma_f32 v22, -v20, v19, v18
	v_fmac_f32_e32 v19, v22, v21
	v_fma_f32 v18, -v20, v19, v18
	v_div_fmas_f32 v18, v18, v21, v19
	v_div_fixup_f32 v2, v18, v2, 1.0
	v_or_b32_e32 v18, 16, v0
	v_mul_lo_u32 v18, v18, s47
	v_or_b32_e32 v18, v18, v172
	v_mul_f32_e32 v19, v58, v2
	v_lshlrev_b32_e32 v18, 1, v18
	v_cvt_pk_bf16_f32 v19, v19, v1
	global_store_short v18, v19, s[42:43]
	v_mul_f32_e32 v19, v42, v2
	v_cvt_pk_bf16_f32 v19, v19, v1
	global_store_short v18, v19, s[42:43] offset:64
	v_mul_f32_e32 v19, v26, v2
	v_cvt_pk_bf16_f32 v19, v19, v1
	global_store_short v18, v19, s[42:43] offset:128
	v_div_scale_f32 v19, s[26:27], v3, v3, 1.0
	v_rcp_f32_e32 v20, v19
	v_mul_f32_e32 v2, v10, v2
	v_cvt_pk_bf16_f32 v2, v2, v1
	global_store_short v18, v2, s[42:43] offset:192
	v_fma_f32 v2, -v19, v20, 1.0
	v_fmac_f32_e32 v20, v2, v20
	v_div_scale_f32 v2, vcc, 1.0, v3, 1.0
	v_mul_f32_e32 v10, v2, v20
	v_fma_f32 v18, -v19, v10, v2
	v_fmac_f32_e32 v10, v18, v20
	v_fma_f32 v2, -v19, v10, v2
	v_div_fmas_f32 v2, v2, v20, v10
	v_div_fixup_f32 v2, v2, v3, 1.0
	v_or_b32_e32 v3, 17, v0
	v_mul_lo_u32 v3, v3, s47
	v_or_b32_e32 v3, v3, v172
	v_mul_f32_e32 v10, v59, v2
	v_lshlrev_b32_e32 v3, 1, v3
	v_cvt_pk_bf16_f32 v10, v10, v1
	global_store_short v3, v10, s[42:43]
	v_mul_f32_e32 v10, v43, v2
	v_cvt_pk_bf16_f32 v10, v10, v1
	global_store_short v3, v10, s[42:43] offset:64
	v_mul_f32_e32 v10, v27, v2
	v_cvt_pk_bf16_f32 v10, v10, v1
	global_store_short v3, v10, s[42:43] offset:128
	v_div_scale_f32 v10, s[26:27], v4, v4, 1.0
	v_rcp_f32_e32 v18, v10
	v_mul_f32_e32 v2, v11, v2
	v_cvt_pk_bf16_f32 v2, v2, v1
	global_store_short v3, v2, s[42:43] offset:192
	v_fma_f32 v2, -v10, v18, 1.0
	v_fmac_f32_e32 v18, v2, v18
	v_div_scale_f32 v2, vcc, 1.0, v4, 1.0
	v_mul_f32_e32 v3, v2, v18
	v_fma_f32 v11, -v10, v3, v2
	v_fmac_f32_e32 v3, v11, v18
	v_fma_f32 v2, -v10, v3, v2
	v_div_fmas_f32 v2, v2, v18, v3
	v_or_b32_e32 v3, 18, v0
	v_div_fixup_f32 v2, v2, v4, 1.0
	v_mul_lo_u32 v3, v3, s47
	v_or_b32_e32 v3, v3, v172
	v_mul_f32_e32 v4, v60, v2
	v_lshlrev_b32_e32 v3, 1, v3
	v_cvt_pk_bf16_f32 v4, v4, v1
	global_store_short v3, v4, s[42:43]
	v_mul_f32_e32 v4, v44, v2
	v_cvt_pk_bf16_f32 v4, v4, v1
	global_store_short v3, v4, s[42:43] offset:64
	v_mul_f32_e32 v4, v28, v2
	v_cvt_pk_bf16_f32 v4, v4, v1
	global_store_short v3, v4, s[42:43] offset:128
	v_div_scale_f32 v4, s[26:27], v5, v5, 1.0
	v_rcp_f32_e32 v10, v4
	v_mul_f32_e32 v2, v12, v2
	v_cvt_pk_bf16_f32 v2, v2, v1
	global_store_short v3, v2, s[42:43] offset:192
	v_fma_f32 v2, -v4, v10, 1.0
	v_fmac_f32_e32 v10, v2, v10
	v_div_scale_f32 v2, vcc, 1.0, v5, 1.0
	v_mul_f32_e32 v3, v2, v10
	v_fma_f32 v11, -v4, v3, v2
	v_fmac_f32_e32 v3, v11, v10
	v_fma_f32 v2, -v4, v3, v2
	v_div_fmas_f32 v2, v2, v10, v3
	v_or_b32_e32 v3, 19, v0
	v_div_fixup_f32 v2, v2, v5, 1.0
	v_mul_lo_u32 v3, v3, s47
	v_or_b32_e32 v3, v3, v172
	v_mul_f32_e32 v4, v61, v2
	v_lshlrev_b32_e32 v3, 1, v3
	v_cvt_pk_bf16_f32 v4, v4, v1
	global_store_short v3, v4, s[42:43]
	v_mul_f32_e32 v4, v45, v2
	v_cvt_pk_bf16_f32 v4, v4, v1
	global_store_short v3, v4, s[42:43] offset:64
	v_mul_f32_e32 v4, v29, v2
	v_cvt_pk_bf16_f32 v4, v4, v1
	v_add_u32_e32 v5, 0x80, v3
	global_store_short v5, v4, s[42:43]
	v_div_scale_f32 v4, s[26:27], v6, v6, 1.0
	v_rcp_f32_e32 v5, v4
	v_mul_f32_e32 v2, v13, v2
	v_cvt_pk_bf16_f32 v2, v2, v1
	v_add_u32_e32 v3, 0xc0, v3
	global_store_short v3, v2, s[42:43]
	v_fma_f32 v2, -v4, v5, 1.0
	v_fmac_f32_e32 v5, v2, v5
	v_div_scale_f32 v2, vcc, 1.0, v6, 1.0
	v_mul_f32_e32 v3, v2, v5
	v_fma_f32 v10, -v4, v3, v2
	v_fmac_f32_e32 v3, v10, v5
	v_fma_f32 v2, -v4, v3, v2
	v_div_fmas_f32 v2, v2, v5, v3
	v_or_b32_e32 v3, 24, v0
	v_div_fixup_f32 v2, v2, v6, 1.0
	v_mul_lo_u32 v3, v3, s47
	v_or_b32_e32 v3, v3, v172
	v_mul_f32_e32 v4, v62, v2
	v_lshlrev_b32_e32 v3, 1, v3
	v_cvt_pk_bf16_f32 v4, v4, v1
	global_store_short v3, v4, s[42:43]
	v_mul_f32_e32 v4, v46, v2
	v_cvt_pk_bf16_f32 v4, v4, v1
	global_store_short v3, v4, s[42:43] offset:64
	v_mul_f32_e32 v4, v30, v2
	v_cvt_pk_bf16_f32 v4, v4, v1
	global_store_short v3, v4, s[42:43] offset:128
	v_div_scale_f32 v4, s[26:27], v7, v7, 1.0
	v_rcp_f32_e32 v5, v4
	v_mul_f32_e32 v2, v14, v2
	v_cvt_pk_bf16_f32 v2, v2, v1
	global_store_short v3, v2, s[42:43] offset:192
	v_fma_f32 v2, -v4, v5, 1.0
	v_fmac_f32_e32 v5, v2, v5
	v_div_scale_f32 v2, vcc, 1.0, v7, 1.0
	v_mul_f32_e32 v3, v2, v5
	v_fma_f32 v6, -v4, v3, v2
	v_fmac_f32_e32 v3, v6, v5
	v_fma_f32 v2, -v4, v3, v2
	v_div_fmas_f32 v2, v2, v5, v3
	v_or_b32_e32 v3, 25, v0
	v_div_fixup_f32 v2, v2, v7, 1.0
	v_mul_lo_u32 v3, v3, s47
	v_or_b32_e32 v3, v3, v172
	v_mul_f32_e32 v4, v63, v2
	v_lshlrev_b32_e32 v3, 1, v3
	v_cvt_pk_bf16_f32 v4, v4, v1
	global_store_short v3, v4, s[42:43]
	v_mul_f32_e32 v4, v47, v2
	v_cvt_pk_bf16_f32 v4, v4, v1
	global_store_short v3, v4, s[42:43] offset:64
	v_mul_f32_e32 v4, v31, v2
	v_cvt_pk_bf16_f32 v4, v4, v1
	global_store_short v3, v4, s[42:43] offset:128
	v_div_scale_f32 v4, s[26:27], v8, v8, 1.0
	v_rcp_f32_e32 v5, v4
	v_mul_f32_e32 v2, v15, v2
	v_cvt_pk_bf16_f32 v2, v2, v1
	global_store_short v3, v2, s[42:43] offset:192
	v_fma_f32 v2, -v4, v5, 1.0
	v_fmac_f32_e32 v5, v2, v5
	v_div_scale_f32 v2, vcc, 1.0, v8, 1.0
	v_mul_f32_e32 v3, v2, v5
	v_fma_f32 v6, -v4, v3, v2
	v_fmac_f32_e32 v3, v6, v5
	v_fma_f32 v2, -v4, v3, v2
	v_div_fmas_f32 v2, v2, v5, v3
	v_or_b32_e32 v3, 26, v0
	v_div_fixup_f32 v2, v2, v8, 1.0
	v_mul_lo_u32 v3, v3, s47
	v_or_b32_e32 v3, v3, v172
	v_mul_f32_e32 v4, v64, v2
	v_lshlrev_b32_e32 v3, 1, v3
	v_cvt_pk_bf16_f32 v4, v4, v1
	global_store_short v3, v4, s[42:43]
	v_mul_f32_e32 v4, v48, v2
	v_cvt_pk_bf16_f32 v4, v4, v1
	global_store_short v3, v4, s[42:43] offset:64
	v_mul_f32_e32 v4, v32, v2
	v_cvt_pk_bf16_f32 v4, v4, v1
	global_store_short v3, v4, s[42:43] offset:128
	v_div_scale_f32 v4, s[26:27], v9, v9, 1.0
	v_rcp_f32_e32 v5, v4
	v_mul_f32_e32 v2, v16, v2
	v_cvt_pk_bf16_f32 v2, v2, v1
	global_store_short v3, v2, s[42:43] offset:192
	v_fma_f32 v2, -v4, v5, 1.0
	v_fmac_f32_e32 v5, v2, v5
	v_div_scale_f32 v2, vcc, 1.0, v9, 1.0
	v_mul_f32_e32 v3, v2, v5
	v_fma_f32 v6, -v4, v3, v2
	v_fmac_f32_e32 v3, v6, v5
	v_fma_f32 v2, -v4, v3, v2
	v_div_fmas_f32 v2, v2, v5, v3
	v_or_b32_e32 v0, 27, v0
	v_div_fixup_f32 v2, v2, v9, 1.0
	v_mul_lo_u32 v0, v0, s47
	v_or_b32_e32 v0, v0, v172
	v_mul_f32_e32 v3, v65, v2
	v_lshlrev_b32_e32 v0, 1, v0
	v_cvt_pk_bf16_f32 v3, v3, v1
	global_store_short v0, v3, s[42:43]
	v_mul_f32_e32 v3, v49, v2
	v_cvt_pk_bf16_f32 v3, v3, v1
	global_store_short v0, v3, s[42:43] offset:64
	v_mul_f32_e32 v3, v33, v2
	v_add_u32_e32 v4, 0x80, v0
	v_mul_f32_e32 v2, v17, v2
	v_add_u32_e32 v0, 0xc0, v0
	s_mov_b64 s[26:27], 0
	v_cvt_pk_bf16_f32 v3, v3, v1
	global_store_short v4, v3, s[42:43]
	v_cvt_pk_bf16_f32 v2, v2, v1
	global_store_short v0, v2, s[42:43]
	s_waitcnt vmcnt(0)
; template <bool FIXED>
; DEVI void attn_task(const bf16_t* __restrict__ Qb, const bf16_t* __restrict__ Kh, const bf16_t* __restrict__ Vh, bf16_t* __restrict__ Ob, char* lds, float shiftC) {
;     ...
;   __syncthreads();
	s_barrier
